# ConvGate store merge cleanup: bf16 converts write straight into the held/staging registers (32 moves gone) and the now-unused per-store address arithmetic of the n=0 sub-blocks removed (25 instruction
# speedup vs baseline: 1.0036x; 1.0036x over previous
.LBB0_113:
	s_or_b64 exec, exec, s[0:1]
	v_ffbh_u32_e32 v0, v135
	v_min_u32_e32 v0, 32, v0
	v_lshlrev_b64 v[114:115], v0, v[134:135]
	v_min_u32_e32 v114, 1, v114
	v_or_b32_e32 v114, v115, v114
	v_cvt_f32_u32_e32 v114, v114
	v_sub_u32_e32 v0, 32, v0
	s_lshl_b32 s5, s78, 7
	v_add_u32_e32 v180, s5, v130
	v_ldexp_f32 v0, v114, v0
	v_fmamk_f32 v0, v0, 0x2e800000, v210
	s_nop 0
	v_rsq_f32_e32 v0, v0
	s_nop 0
	s_nop 0
	v_mov_b32_e32 v178, v0
	v_ffbh_u32_e32 v0, v133
	v_min_u32_e32 v0, 32, v0
	v_pk_mul_f32 v[186:187], v[110:111], v[178:179] op_sel_hi:[1,0]
	v_lshlrev_b64 v[110:111], v0, v[132:133]
	v_min_u32_e32 v110, 1, v110
	v_or_b32_e32 v110, v111, v110
	v_cvt_f32_u32_e32 v110, v110
	v_sub_u32_e32 v0, 32, v0
	v_pk_mul_f32 v[184:185], v[112:113], v[178:179] op_sel_hi:[1,0]
	v_ldexp_f32 v0, v110, v0
	v_fmamk_f32 v0, v0, 0x2e800000, v210
	s_nop 0
	v_rsq_f32_e32 v0, v0
	s_nop 0
	s_nop 0
	v_mov_b32_e32 v182, v0
	v_pk_mul_f32 v[188:189], v[108:109], v[182:183] op_sel_hi:[1,0]
	v_pk_mul_f32 v[198:199], v[106:107], v[182:183] op_sel_hi:[1,0]
	v_ashrrev_i32_e32 v181, 31, v180
	v_lshlrev_b64 v[118:119], 2, v[180:181]
	v_lshl_add_u64 v[106:107], s[44:45], 0, v[118:119]
	v_lshl_add_u64 v[108:109], s[60:61], 0, v[118:119]
	global_load_dwordx4 v[122:125], v[106:107], off
	global_load_dwordx4 v[126:129], v[108:109], off
	v_lshl_add_u64 v[106:107], s[2:3], 0, v[118:119]
	global_load_dwordx4 v[130:133], v[106:107], off
	v_lshl_add_u64 v[106:107], s[48:49], 0, v[118:119]
	global_load_dwordx4 v[134:137], v[106:107], off
	s_nop 1
	v_cmp_lt_u32_e32 vcc, 1, v183
	v_mov_b32_dpp v206, v170 row_ror:1 row_mask:0xf bank_mask:0xf
	v_mov_b32_dpp v204, v170 row_ror:2 row_mask:0xf bank_mask:0xf
	v_mov_b32_dpp v207, v171 row_ror:1 row_mask:0xf bank_mask:0xf
	v_mov_b32_dpp v205, v171 row_ror:2 row_mask:0xf bank_mask:0xf
	v_mov_b32_dpp v202, v172 row_ror:1 row_mask:0xf bank_mask:0xf
	v_mov_b32_dpp v200, v172 row_ror:2 row_mask:0xf bank_mask:0xf
	v_mov_b32_dpp v203, v173 row_ror:1 row_mask:0xf bank_mask:0xf
	v_mov_b32_dpp v201, v173 row_ror:2 row_mask:0xf bank_mask:0xf
	v_mov_b32_dpp v241, v186 row_ror:1 row_mask:0xf bank_mask:0xf
	v_mov_b32_dpp v240, v186 row_ror:2 row_mask:0xf bank_mask:0xf
	v_mov_b32_dpp v245, v187 row_ror:1 row_mask:0xf bank_mask:0xf
	v_mov_b32_dpp v244, v187 row_ror:2 row_mask:0xf bank_mask:0xf
	v_mov_b32_dpp v229, v184 row_ror:1 row_mask:0xf bank_mask:0xf
	v_mov_b32_dpp v228, v184 row_ror:2 row_mask:0xf bank_mask:0xf
	v_mov_b32_dpp v235, v185 row_ror:1 row_mask:0xf bank_mask:0xf
	v_mov_b32_dpp v233, v185 row_ror:2 row_mask:0xf bank_mask:0xf
	v_mov_b32_dpp v234, v198 row_ror:1 row_mask:0xf bank_mask:0xf
	v_mov_b32_dpp v231, v198 row_ror:2 row_mask:0xf bank_mask:0xf
	v_mov_b32_dpp v239, v199 row_ror:1 row_mask:0xf bank_mask:0xf
	v_mov_b32_dpp v237, v199 row_ror:2 row_mask:0xf bank_mask:0xf
	v_mov_b32_dpp v151, v188 row_ror:1 row_mask:0xf bank_mask:0xf
	v_mov_b32_dpp v0, v188 row_ror:2 row_mask:0xf bank_mask:0xf
	v_mov_b32_dpp v227, v189 row_ror:1 row_mask:0xf bank_mask:0xf
	v_mov_b32_dpp v213, v189 row_ror:2 row_mask:0xf bank_mask:0xf
	v_mov_b32_dpp v243, v176 row_ror:1 row_mask:0xf bank_mask:0xf
	v_mov_b32_dpp v242, v176 row_ror:2 row_mask:0xf bank_mask:0xf
	v_mov_b32_dpp v247, v177 row_ror:1 row_mask:0xf bank_mask:0xf
	v_mov_b32_dpp v246, v177 row_ror:2 row_mask:0xf bank_mask:0xf
	v_mov_b32_dpp v232, v174 row_ror:1 row_mask:0xf bank_mask:0xf
	v_mov_b32_dpp v230, v174 row_ror:2 row_mask:0xf bank_mask:0xf
	v_mov_b32_dpp v238, v175 row_ror:1 row_mask:0xf bank_mask:0xf
	v_mov_b32_dpp v236, v175 row_ror:2 row_mask:0xf bank_mask:0xf
	v_lshl_add_u64 v[106:107], s[96:97], 0, v[118:119]
	v_lshl_add_u64 v[108:109], s[62:63], 0, v[118:119]
	global_load_dwordx4 v[114:117], v[106:107], off
	global_load_dwordx4 v[110:113], v[108:109], off
	v_lshl_add_u64 v[106:107], s[64:65], 0, v[118:119]
	v_lshl_add_u64 v[118:119], s[66:67], 0, v[118:119]
	global_load_dwordx4 v[106:109], v[106:107], off
	s_nop 1
	global_load_dwordx4 v[118:121], v[118:119], off
	s_nop 1
	v_mov_b32_dpp v190, v158 row_ror:1 row_mask:0xf bank_mask:0xf
	v_mov_b32_dpp v194, v158 row_ror:2 row_mask:0xf bank_mask:0xf
	v_mov_b32_dpp v191, v159 row_ror:1 row_mask:0xf bank_mask:0xf
	v_mov_b32_dpp v195, v159 row_ror:2 row_mask:0xf bank_mask:0xf
	v_mov_b32_dpp v192, v156 row_ror:1 row_mask:0xf bank_mask:0xf
	v_mov_b32_dpp v196, v156 row_ror:2 row_mask:0xf bank_mask:0xf
	v_mov_b32_dpp v193, v157 row_ror:1 row_mask:0xf bank_mask:0xf
	v_mov_b32_dpp v197, v157 row_ror:2 row_mask:0xf bank_mask:0xf
	s_and_saveexec_b64 s[0:1], vcc
	s_mov_b32 s50, 0x20000
	s_mov_b32 s47, 0xbfb8aa3b
	s_cbranch_execz .Lcg_skip0
	s_waitcnt vmcnt(4)
	v_pk_fma_f32 v[248:249], v[124:125], v[200:201], v[136:137]
	s_nop 0
	v_pk_fma_f32 v[248:249], v[128:129], v[202:203], v[248:249]
	s_nop 0
	v_pk_fma_f32 v[172:173], v[172:173], v[132:133], v[248:249]
	v_pk_fma_f32 v[248:249], v[122:123], v[204:205], v[134:135]
	v_pk_fma_f32 v[248:249], v[126:127], v[206:207], v[248:249]
	v_pk_fma_f32 v[170:171], v[170:171], v[130:131], v[248:249]
	v_pk_mul_f32 v[248:249], v[170:171], s[98:99] op_sel_hi:[1,0]
	v_pk_mul_f32 v[250:251], v[172:173], s[98:99] op_sel_hi:[1,0]
	v_exp_f32_e32 v248, v248
	v_exp_f32_e32 v249, v249
	v_exp_f32_e32 v250, v250
	v_exp_f32_e32 v251, v251
	v_pk_add_f32 v[248:249], v[248:249], 1.0 op_sel_hi:[1,0]
	v_pk_add_f32 v[250:251], v[250:251], 1.0 op_sel_hi:[1,0]
	v_rcp_f32_e32 v248, v248
	v_rcp_f32_e32 v249, v249
	v_rcp_f32_e32 v250, v250
	v_rcp_f32_e32 v251, v251
	v_pk_mul_f32 v[170:171], v[170:171], v[248:249]
	v_pk_mul_f32 v[172:173], v[172:173], v[250:251]
	s_waitcnt vmcnt(0)
	v_pk_fma_f32 v[248:249], v[116:117], v[196:197], v[120:121]
	v_pk_fma_f32 v[250:251], v[114:115], v[194:195], v[118:119]
	v_pk_fma_f32 v[248:249], v[112:113], v[192:193], v[248:249]
	v_pk_fma_f32 v[250:251], v[110:111], v[190:191], v[250:251]
	v_pk_fma_f32 v[156:157], v[156:157], v[108:109], v[248:249]
	v_pk_fma_f32 v[158:159], v[158:159], v[106:107], v[250:251]
	v_pk_mul_f32 v[156:157], v[172:173], v[156:157]
	v_pk_mul_f32 v[158:159], v[170:171], v[158:159]
	s_nop 0
	v_cvt_pk_bf16_f32 v248, v158, v159
	v_cvt_pk_bf16_f32 v249, v156, v157
.LBB0_115:
	s_or_b64 exec, exec, s[0:1]
	v_cmp_eq_u32_e64 s[42:43], 0, v183
	v_cndmask_b32_e32 v159, v205, v244, vcc
	v_cndmask_b32_e32 v158, v204, v240, vcc
	v_cndmask_b32_e64 v157, v245, v207, s[42:43]
	v_cndmask_b32_e64 v156, v241, v206, s[42:43]
	s_waitcnt vmcnt(4)
	v_pk_fma_f32 v[158:159], v[122:123], v[158:159], v[134:135]
	v_cndmask_b32_e32 v173, v201, v233, vcc
	v_cndmask_b32_e32 v172, v200, v228, vcc
	v_pk_fma_f32 v[156:157], v[126:127], v[156:157], v[158:159]
	v_cndmask_b32_e64 v171, v235, v203, s[42:43]
	v_cndmask_b32_e64 v170, v229, v202, s[42:43]
	v_pk_fma_f32 v[172:173], v[124:125], v[172:173], v[136:137]
	v_pk_fma_f32 v[156:157], v[186:187], v[130:131], v[156:157]
	v_pk_fma_f32 v[170:171], v[128:129], v[170:171], v[172:173]
	v_cndmask_b32_e32 v187, v244, v237, vcc
	v_cndmask_b32_e32 v186, v240, v231, vcc
	v_pk_fma_f32 v[170:171], v[184:185], v[132:133], v[170:171]
	v_cndmask_b32_e64 v185, v239, v245, s[42:43]
	v_cndmask_b32_e64 v184, v234, v241, s[42:43]
	v_pk_fma_f32 v[186:187], v[122:123], v[186:187], v[134:135]
	v_cndmask_b32_e32 v201, v233, v213, vcc
	v_pk_fma_f32 v[184:185], v[126:127], v[184:185], v[186:187]
	v_cndmask_b32_e32 v200, v228, v0, vcc
	v_pk_fma_f32 v[184:185], v[198:199], v[130:131], v[184:185]
	v_cndmask_b32_e64 v199, v227, v235, s[42:43]
	v_cndmask_b32_e64 v198, v151, v229, s[42:43]
	v_pk_fma_f32 v[200:201], v[124:125], v[200:201], v[136:137]
	v_cndmask_b32_e32 v203, v237, v246, vcc
	v_cndmask_b32_e32 v202, v231, v242, vcc
	v_pk_fma_f32 v[198:199], v[128:129], v[198:199], v[200:201]
	v_cndmask_b32_e64 v201, v247, v239, s[42:43]
	v_cndmask_b32_e64 v200, v243, v234, s[42:43]
	v_pk_fma_f32 v[122:123], v[122:123], v[202:203], v[134:135]
	v_cndmask_b32_e32 v135, v213, v236, vcc
	v_pk_fma_f32 v[122:123], v[126:127], v[200:201], v[122:123]
	v_cndmask_b32_e32 v134, v0, v230, vcc
	v_pk_fma_f32 v[122:123], v[176:177], v[130:131], v[122:123]
	v_cndmask_b32_e64 v131, v238, v227, s[42:43]
	v_cndmask_b32_e64 v130, v232, v151, s[42:43]
	v_pk_fma_f32 v[124:125], v[124:125], v[134:135], v[136:137]
	v_pk_fma_f32 v[124:125], v[128:129], v[130:131], v[124:125]
	v_mov_b32_e32 v179, v178
	v_pk_fma_f32 v[124:125], v[174:175], v[132:133], v[124:125]
	v_mov_b32_e32 v183, v182
	v_mov_b32_e32 v130, v178
	v_mov_b32_e32 v131, v178
	v_pk_mul_f32 v[104:105], v[104:105], v[130:131]
	v_pk_mul_f32 v[102:103], v[102:103], v[178:179]
	v_pk_mul_f32 v[98:99], v[98:99], v[182:183]
	s_nop 1
	v_mov_b32_e32 v130, v182
	v_mov_b32_e32 v131, v182
	s_nop 1
	v_mov_b32_dpp v177, v102 row_ror:2 row_mask:0xf bank_mask:0xf
	s_nop 1
	v_mov_b32_dpp v179, v103 row_ror:2 row_mask:0xf bank_mask:0xf
	s_nop 1
	v_mov_b32_dpp v183, v104 row_ror:2 row_mask:0xf bank_mask:0xf
	s_nop 1
	v_mov_b32_dpp v201, v105 row_ror:2 row_mask:0xf bank_mask:0xf
	v_pk_fma_f32 v[188:189], v[188:189], v[132:133], v[198:199]
	v_pk_mul_f32 v[100:101], v[100:101], v[130:131]
	v_mov_b32_dpp v176, v102 row_ror:1 row_mask:0xf bank_mask:0xf
	v_mov_b32_dpp v178, v103 row_ror:1 row_mask:0xf bank_mask:0xf
	v_mov_b32_dpp v182, v104 row_ror:1 row_mask:0xf bank_mask:0xf
	v_mov_b32_dpp v200, v105 row_ror:1 row_mask:0xf bank_mask:0xf
	v_cndmask_b32_e32 v130, v194, v177, vcc
	v_cndmask_b32_e32 v131, v195, v179, vcc
	v_cndmask_b32_e32 v132, v196, v183, vcc
	v_cndmask_b32_e32 v133, v197, v201, vcc
	v_cndmask_b32_e64 v134, v176, v190, s[42:43]
	v_cndmask_b32_e64 v135, v178, v191, s[42:43]
	v_cndmask_b32_e64 v136, v182, v192, s[42:43]
	v_cndmask_b32_e64 v137, v200, v193, s[42:43]
	s_waitcnt vmcnt(1)
	v_pk_fma_f32 v[132:133], v[116:117], v[132:133], v[120:121]
	v_pk_fma_f32 v[130:131], v[114:115], v[130:131], v[118:119]
	v_pk_fma_f32 v[132:133], v[112:113], v[136:137], v[132:133]
	v_pk_fma_f32 v[130:131], v[110:111], v[134:135], v[130:131]
	v_pk_mul_f32 v[158:159], v[156:157], s[98:99] op_sel_hi:[1,0]
	v_pk_mul_f32 v[172:173], v[170:171], s[98:99] op_sel_hi:[1,0]
	v_exp_f32_e32 v158, v158
	v_exp_f32_e32 v159, v159
	v_exp_f32_e32 v172, v172
	v_exp_f32_e32 v173, v173
	v_pk_add_f32 v[158:159], v[158:159], 1.0 op_sel_hi:[1,0]
	v_pk_add_f32 v[172:173], v[172:173], 1.0 op_sel_hi:[1,0]
	v_rcp_f32_e32 v158, v158
	v_rcp_f32_e32 v159, v159
	v_rcp_f32_e32 v172, v172
	v_rcp_f32_e32 v173, v173
	v_pk_mul_f32 v[150:151], v[156:157], v[158:159]
	v_pk_mul_f32 v[156:157], v[170:171], v[172:173]
	v_pk_fma_f32 v[104:105], v[104:105], v[108:109], v[132:133]
	v_pk_fma_f32 v[102:103], v[102:103], v[106:107], v[130:131]
	v_pk_mul_f32 v[104:105], v[156:157], v[104:105]
	v_pk_mul_f32 v[102:103], v[150:151], v[102:103]
	v_cvt_pk_bf16_f32 v250, v102, v103
	v_cvt_pk_bf16_f32 v251, v104, v105
	s_nop 1
	s_nop 1
	v_mov_b32_dpp v158, v98 row_ror:2 row_mask:0xf bank_mask:0xf
	s_nop 1
	v_mov_b32_dpp v170, v99 row_ror:2 row_mask:0xf bank_mask:0xf
	s_nop 1
	v_mov_b32_dpp v172, v100 row_ror:2 row_mask:0xf bank_mask:0xf
	s_nop 1
	v_mov_b32_dpp v180, v101 row_ror:2 row_mask:0xf bank_mask:0xf
	v_mov_b32_dpp v0, v98 row_ror:1 row_mask:0xf bank_mask:0xf
	v_mov_b32_dpp v159, v99 row_ror:1 row_mask:0xf bank_mask:0xf
	v_mov_b32_dpp v171, v100 row_ror:1 row_mask:0xf bank_mask:0xf
	v_mov_b32_dpp v173, v101 row_ror:1 row_mask:0xf bank_mask:0xf
	v_cndmask_b32_e32 v102, v177, v158, vcc
	v_cndmask_b32_e32 v103, v179, v170, vcc
	v_cndmask_b32_e32 v130, v183, v172, vcc
	v_cndmask_b32_e32 v131, v201, v180, vcc
	v_cndmask_b32_e64 v134, v0, v176, s[42:43]
	v_cndmask_b32_e64 v135, v159, v178, s[42:43]
	v_cndmask_b32_e64 v136, v171, v182, s[42:43]
	v_cndmask_b32_e64 v137, v173, v200, s[42:43]
	v_pk_fma_f32 v[130:131], v[116:117], v[130:131], v[120:121]
	v_pk_fma_f32 v[102:103], v[114:115], v[102:103], v[118:119]
	v_pk_fma_f32 v[130:131], v[112:113], v[136:137], v[130:131]
	v_pk_fma_f32 v[102:103], v[110:111], v[134:135], v[102:103]
	v_pk_mul_f32 v[186:187], v[184:185], s[98:99] op_sel_hi:[1,0]
	v_pk_mul_f32 v[198:199], v[188:189], s[98:99] op_sel_hi:[1,0]
	v_exp_f32_e32 v186, v186
	v_exp_f32_e32 v187, v187
	v_exp_f32_e32 v198, v198
	v_exp_f32_e32 v199, v199
	v_pk_add_f32 v[186:187], v[186:187], 1.0 op_sel_hi:[1,0]
	v_pk_add_f32 v[198:199], v[198:199], 1.0 op_sel_hi:[1,0]
	v_rcp_f32_e32 v186, v186
	v_rcp_f32_e32 v187, v187
	v_rcp_f32_e32 v198, v198
	v_rcp_f32_e32 v199, v199
	v_pk_mul_f32 v[150:151], v[184:185], v[186:187]
	v_pk_mul_f32 v[156:157], v[188:189], v[198:199]
	v_pk_fma_f32 v[100:101], v[100:101], v[108:109], v[130:131]
	v_pk_fma_f32 v[98:99], v[98:99], v[106:107], v[102:103]
	v_pk_mul_f32 v[100:101], v[156:157], v[100:101]
	v_pk_mul_f32 v[98:99], v[150:151], v[98:99]
	v_cvt_pk_bf16_f32 v244, v98, v99
	v_cvt_pk_bf16_f32 v245, v100, v101
	s_nop 1
	s_nop 1
	v_mov_b32_dpp v98, v154 row_ror:2 row_mask:0xf bank_mask:0xf
	s_nop 1
	v_mov_b32_dpp v99, v155 row_ror:2 row_mask:0xf bank_mask:0xf
	s_nop 1
	v_mov_b32_dpp v100, v152 row_ror:2 row_mask:0xf bank_mask:0xf
	s_nop 1
	v_mov_b32_dpp v101, v153 row_ror:2 row_mask:0xf bank_mask:0xf
	v_mov_b32_dpp v102, v154 row_ror:1 row_mask:0xf bank_mask:0xf
	v_mov_b32_dpp v103, v155 row_ror:1 row_mask:0xf bank_mask:0xf
	v_mov_b32_dpp v130, v152 row_ror:1 row_mask:0xf bank_mask:0xf
	v_mov_b32_dpp v131, v153 row_ror:1 row_mask:0xf bank_mask:0xf
	v_cndmask_b32_e32 v98, v158, v98, vcc
	v_cndmask_b32_e32 v99, v170, v99, vcc
	v_cndmask_b32_e32 v100, v172, v100, vcc
	v_cndmask_b32_e32 v101, v180, v101, vcc
	v_cndmask_b32_e64 v102, v102, v0, s[42:43]
	v_cndmask_b32_e64 v103, v103, v159, s[42:43]
	v_cndmask_b32_e64 v130, v130, v171, s[42:43]
	v_cndmask_b32_e64 v131, v131, v173, s[42:43]
	v_pk_fma_f32 v[98:99], v[114:115], v[98:99], v[118:119]
	v_pk_fma_f32 v[100:101], v[116:117], v[100:101], v[120:121]
	v_pk_fma_f32 v[98:99], v[110:111], v[102:103], v[98:99]
	v_pk_fma_f32 v[100:101], v[112:113], v[130:131], v[100:101]
	v_pk_mul_f32 v[126:127], v[122:123], s[98:99] op_sel_hi:[1,0]
	v_pk_mul_f32 v[128:129], v[124:125], s[98:99] op_sel_hi:[1,0]
	v_exp_f32_e32 v126, v126
	v_exp_f32_e32 v127, v127
	v_exp_f32_e32 v128, v128
	v_exp_f32_e32 v129, v129
	v_pk_add_f32 v[126:127], v[126:127], 1.0 op_sel_hi:[1,0]
	v_pk_add_f32 v[128:129], v[128:129], 1.0 op_sel_hi:[1,0]
	v_rcp_f32_e32 v126, v126
	v_rcp_f32_e32 v127, v127
	v_rcp_f32_e32 v128, v128
	v_rcp_f32_e32 v129, v129
	v_pk_mul_f32 v[122:123], v[122:123], v[126:127]
	v_pk_mul_f32 v[124:125], v[124:125], v[128:129]
	v_pk_fma_f32 v[98:99], v[154:155], v[106:107], v[98:99]
	v_pk_fma_f32 v[100:101], v[152:153], v[108:109], v[100:101]
	v_pk_mul_f32 v[98:99], v[122:123], v[98:99]
	v_pk_mul_f32 v[100:101], v[124:125], v[100:101]
	v_cvt_pk_bf16_f32 v246, v98, v99
	s_nop 0
	v_cvt_pk_bf16_f32 v247, v100, v101
	s_add_i32 s0, s6, 2
	v_and_b32_e32 v129, 15, v226
	v_or_b32_e32 v106, s4, v129
	v_ashrrev_i32_e32 v107, 31, v106
	v_lshl_add_u64 v[104:105], v[106:107], 3, s[38:39]
	global_load_dwordx2 v[108:109], v[104:105], off offset:1024
	global_load_dwordx2 v[102:103], v[104:105], off offset:1152
	global_load_dwordx2 v[100:101], v[104:105], off offset:1280
	s_nop 0
	global_load_dwordx2 v[104:105], v[104:105], off offset:1408
	v_ashrrev_i32_e32 v0, 1, v226
	v_and_b32_e32 v0, -8, v0
	v_add_u32_e32 v98, s21, v0
	s_mul_hi_i32 s1, s0, 0xb000
	s_mul_i32 s0, s0, 0xb000
	s_add_u32 s0, s18, s0
	s_addc_u32 s1, s19, s1
	s_add_u32 s78, s0, s80
	s_addc_u32 s79, s1, s81
	s_waitcnt vmcnt(3)
	v_ffbh_u32_e32 v0, v109
	v_min_u32_e32 v0, 32, v0
	v_lshlrev_b64 v[108:109], v0, v[108:109]
	v_min_u32_e32 v99, 1, v108
	v_or_b32_e32 v99, v109, v99
	v_cvt_f32_u32_e32 v99, v99
	v_sub_u32_e32 v0, 32, v0
	v_ldexp_f32 v0, v99, v0
	v_fmamk_f32 v0, v0, 0x2e800000, v210
	s_nop 0
	v_rsq_f32_e32 v0, v0
	s_nop 0
	s_nop 0
	v_ashrrev_i32_e32 v99, 31, v98
	v_pk_mul_f32 v[118:119], v[96:97], v[0:1] op_sel_hi:[1,0]
	v_pk_mul_f32 v[116:117], v[94:95], v[0:1] op_sel_hi:[1,0]
	v_pk_mul_f32 v[112:113], v[92:93], v[0:1] op_sel_hi:[1,0]
	v_pk_mul_f32 v[114:115], v[90:91], v[0:1] op_sel_hi:[1,0]
	v_lshl_add_u64 v[90:91], v[98:99], 1, s[78:79]
	v_cmp_gt_u32_e32 vcc, 2, v129
	s_and_saveexec_b64 s[0:1], vcc
	s_cbranch_execz .LBB0_117
	v_mul_u32_u24_e32 v0, 0x1600, v129
	v_lshlrev_b32_e32 v0, 1, v0
	v_cvt_pk_bf16_f32 v92, v116, v117
	v_cvt_pk_bf16_f32 v93, v118, v119
	v_lshl_add_u64 v[96:97], v[90:91], 0, v[0:1]
	v_cvt_pk_bf16_f32 v94, v114, v115
	v_cvt_pk_bf16_f32 v95, v112, v113
	global_store_dwordx2 v[96:97], v[92:93], off
	global_store_dwordx2 v[96:97], v[94:95], off offset:256

.LBB0_119:
	s_or_b64 exec, exec, s[0:1]
	v_ffbh_u32_e32 v0, v103
	v_min_u32_e32 v0, 32, v0
	v_lshlrev_b64 v[82:83], v0, v[102:103]
	v_min_u32_e32 v82, 1, v82
	v_or_b32_e32 v82, v83, v82
	v_cvt_f32_u32_e32 v82, v82
	v_sub_u32_e32 v0, 32, v0
	v_add_u32_e32 v126, s5, v98
	v_ldexp_f32 v0, v82, v0
	v_fmamk_f32 v0, v0, 0x2e800000, v210
	s_nop 0
	v_rsq_f32_e32 v0, v0
	s_nop 0
	s_nop 0
	v_mov_b32_e32 v124, v0
	v_ffbh_u32_e32 v0, v101
	v_min_u32_e32 v0, 32, v0
	v_pk_mul_f32 v[132:133], v[78:79], v[124:125] op_sel_hi:[1,0]
	v_lshlrev_b64 v[78:79], v0, v[100:101]
	v_min_u32_e32 v78, 1, v78
	v_or_b32_e32 v78, v79, v78
	v_cvt_f32_u32_e32 v78, v78
	v_sub_u32_e32 v0, 32, v0
	v_pk_mul_f32 v[130:131], v[80:81], v[124:125] op_sel_hi:[1,0]
	v_ldexp_f32 v0, v78, v0
	v_fmamk_f32 v0, v0, 0x2e800000, v210
	s_nop 0
	v_rsq_f32_e32 v0, v0
	s_nop 0
	s_nop 0
	v_mov_b32_e32 v128, v0
	v_pk_mul_f32 v[134:135], v[76:77], v[128:129] op_sel_hi:[1,0]
	v_pk_mul_f32 v[156:157], v[74:75], v[128:129] op_sel_hi:[1,0]
	v_ashrrev_i32_e32 v127, 31, v126
	v_lshlrev_b64 v[86:87], 2, v[126:127]
	v_lshl_add_u64 v[74:75], s[44:45], 0, v[86:87]
	v_lshl_add_u64 v[76:77], s[60:61], 0, v[86:87]
	global_load_dwordx4 v[90:93], v[74:75], off
	global_load_dwordx4 v[94:97], v[76:77], off
	v_lshl_add_u64 v[74:75], s[2:3], 0, v[86:87]
	global_load_dwordx4 v[98:101], v[74:75], off
	v_lshl_add_u64 v[74:75], s[48:49], 0, v[86:87]
	global_load_dwordx4 v[102:105], v[74:75], off
	s_nop 1
	v_cmp_lt_u32_e32 vcc, 1, v129
	v_mov_b32_dpp v174, v116 row_ror:1 row_mask:0xf bank_mask:0xf
	v_mov_b32_dpp v172, v116 row_ror:2 row_mask:0xf bank_mask:0xf
	v_mov_b32_dpp v175, v117 row_ror:1 row_mask:0xf bank_mask:0xf
	v_mov_b32_dpp v173, v117 row_ror:2 row_mask:0xf bank_mask:0xf
	v_mov_b32_dpp v170, v118 row_ror:1 row_mask:0xf bank_mask:0xf
	v_mov_b32_dpp v158, v118 row_ror:2 row_mask:0xf bank_mask:0xf
	v_mov_b32_dpp v171, v119 row_ror:1 row_mask:0xf bank_mask:0xf
	v_mov_b32_dpp v159, v119 row_ror:2 row_mask:0xf bank_mask:0xf
	v_mov_b32_dpp v191, v132 row_ror:1 row_mask:0xf bank_mask:0xf
	v_mov_b32_dpp v190, v132 row_ror:2 row_mask:0xf bank_mask:0xf
	v_mov_b32_dpp v195, v133 row_ror:1 row_mask:0xf bank_mask:0xf
	v_mov_b32_dpp v194, v133 row_ror:2 row_mask:0xf bank_mask:0xf
	v_mov_b32_dpp v179, v130 row_ror:1 row_mask:0xf bank_mask:0xf
	v_mov_b32_dpp v178, v130 row_ror:2 row_mask:0xf bank_mask:0xf
	v_mov_b32_dpp v185, v131 row_ror:1 row_mask:0xf bank_mask:0xf
	v_mov_b32_dpp v183, v131 row_ror:2 row_mask:0xf bank_mask:0xf
	v_mov_b32_dpp v184, v156 row_ror:1 row_mask:0xf bank_mask:0xf
	v_mov_b32_dpp v181, v156 row_ror:2 row_mask:0xf bank_mask:0xf
	v_mov_b32_dpp v189, v157 row_ror:1 row_mask:0xf bank_mask:0xf
	v_mov_b32_dpp v187, v157 row_ror:2 row_mask:0xf bank_mask:0xf
	v_mov_b32_dpp v107, v134 row_ror:1 row_mask:0xf bank_mask:0xf
	v_mov_b32_dpp v0, v134 row_ror:2 row_mask:0xf bank_mask:0xf
	v_mov_b32_dpp v177, v135 row_ror:1 row_mask:0xf bank_mask:0xf
	v_mov_b32_dpp v176, v135 row_ror:2 row_mask:0xf bank_mask:0xf
	v_mov_b32_dpp v193, v122 row_ror:1 row_mask:0xf bank_mask:0xf
	v_mov_b32_dpp v192, v122 row_ror:2 row_mask:0xf bank_mask:0xf
	v_mov_b32_dpp v197, v123 row_ror:1 row_mask:0xf bank_mask:0xf
	v_mov_b32_dpp v196, v123 row_ror:2 row_mask:0xf bank_mask:0xf
	v_mov_b32_dpp v182, v120 row_ror:1 row_mask:0xf bank_mask:0xf
	v_mov_b32_dpp v180, v120 row_ror:2 row_mask:0xf bank_mask:0xf
	v_mov_b32_dpp v188, v121 row_ror:1 row_mask:0xf bank_mask:0xf
	v_mov_b32_dpp v186, v121 row_ror:2 row_mask:0xf bank_mask:0xf
	v_lshl_add_u64 v[74:75], s[96:97], 0, v[86:87]
	v_lshl_add_u64 v[76:77], s[62:63], 0, v[86:87]
	global_load_dwordx4 v[82:85], v[74:75], off
	global_load_dwordx4 v[78:81], v[76:77], off
	v_lshl_add_u64 v[74:75], s[64:65], 0, v[86:87]
	v_lshl_add_u64 v[86:87], s[66:67], 0, v[86:87]
	global_load_dwordx4 v[74:77], v[74:75], off
	s_nop 1
	global_load_dwordx4 v[86:89], v[86:87], off
	s_nop 1
	v_mov_b32_dpp v136, v114 row_ror:1 row_mask:0xf bank_mask:0xf
	v_mov_b32_dpp v152, v114 row_ror:2 row_mask:0xf bank_mask:0xf
	v_mov_b32_dpp v137, v115 row_ror:1 row_mask:0xf bank_mask:0xf
	v_mov_b32_dpp v153, v115 row_ror:2 row_mask:0xf bank_mask:0xf
	v_mov_b32_dpp v150, v112 row_ror:1 row_mask:0xf bank_mask:0xf
	v_mov_b32_dpp v154, v112 row_ror:2 row_mask:0xf bank_mask:0xf
	v_mov_b32_dpp v151, v113 row_ror:1 row_mask:0xf bank_mask:0xf
	v_mov_b32_dpp v155, v113 row_ror:2 row_mask:0xf bank_mask:0xf
	s_and_saveexec_b64 s[0:1], vcc
	s_cbranch_execz .Lcg_skip1
	s_waitcnt vmcnt(4)
	v_pk_fma_f32 v[198:199], v[92:93], v[158:159], v[104:105]
	s_nop 0
	v_pk_fma_f32 v[198:199], v[96:97], v[170:171], v[198:199]
	s_nop 0
	v_pk_fma_f32 v[118:119], v[118:119], v[100:101], v[198:199]
	v_pk_fma_f32 v[198:199], v[90:91], v[172:173], v[102:103]
	v_pk_fma_f32 v[198:199], v[94:95], v[174:175], v[198:199]
	v_pk_fma_f32 v[116:117], v[116:117], v[98:99], v[198:199]
	v_add_u32_e32 v125, 0x80, v106
	v_pk_mul_f32 v[198:199], v[116:117], s[98:99] op_sel_hi:[1,0]
	v_pk_mul_f32 v[200:201], v[118:119], s[98:99] op_sel_hi:[1,0]
	v_exp_f32_e32 v198, v198
	v_exp_f32_e32 v199, v199
	v_exp_f32_e32 v200, v200
	v_exp_f32_e32 v201, v201
	v_pk_add_f32 v[198:199], v[198:199], 1.0 op_sel_hi:[1,0]
	v_pk_add_f32 v[200:201], v[200:201], 1.0 op_sel_hi:[1,0]
	v_rcp_f32_e32 v198, v198
	v_rcp_f32_e32 v199, v199
	v_rcp_f32_e32 v200, v200
	v_rcp_f32_e32 v201, v201
	v_pk_mul_f32 v[116:117], v[116:117], v[198:199]
	v_pk_mul_f32 v[118:119], v[118:119], v[200:201]
	s_waitcnt vmcnt(0)
	v_pk_fma_f32 v[198:199], v[84:85], v[154:155], v[88:89]
	v_pk_fma_f32 v[200:201], v[82:83], v[152:153], v[86:87]
	v_pk_fma_f32 v[198:199], v[80:81], v[150:151], v[198:199]
	v_pk_fma_f32 v[200:201], v[78:79], v[136:137], v[200:201]
	v_pk_fma_f32 v[112:113], v[112:113], v[76:77], v[198:199]
	v_pk_fma_f32 v[114:115], v[114:115], v[74:75], v[200:201]
	v_pk_mul_f32 v[112:113], v[118:119], v[112:113]
	v_pk_mul_f32 v[114:115], v[116:117], v[114:115]
	s_nop 0
	v_cvt_pk_bf16_f32 v228, v114, v115
	v_cvt_pk_bf16_f32 v229, v112, v113
.LBB0_121:
	s_or_b64 exec, exec, s[0:1]
	v_cmp_eq_u32_e64 s[42:43], 0, v129
	v_cndmask_b32_e32 v115, v173, v194, vcc
	v_cndmask_b32_e32 v114, v172, v190, vcc
	v_cndmask_b32_e64 v113, v195, v175, s[42:43]
	v_cndmask_b32_e64 v112, v191, v174, s[42:43]
	s_waitcnt vmcnt(4)
	v_pk_fma_f32 v[114:115], v[90:91], v[114:115], v[102:103]
	v_cndmask_b32_e32 v119, v159, v183, vcc
	v_cndmask_b32_e32 v118, v158, v178, vcc
	v_pk_fma_f32 v[112:113], v[94:95], v[112:113], v[114:115]
	v_cndmask_b32_e64 v117, v185, v171, s[42:43]
	v_cndmask_b32_e64 v116, v179, v170, s[42:43]
	v_pk_fma_f32 v[118:119], v[92:93], v[118:119], v[104:105]
	v_pk_fma_f32 v[112:113], v[132:133], v[98:99], v[112:113]
	v_pk_fma_f32 v[116:117], v[96:97], v[116:117], v[118:119]
	v_cndmask_b32_e32 v133, v194, v187, vcc
	v_cndmask_b32_e32 v132, v190, v181, vcc
	v_pk_fma_f32 v[116:117], v[130:131], v[100:101], v[116:117]
	v_cndmask_b32_e64 v131, v189, v195, s[42:43]
	v_cndmask_b32_e64 v130, v184, v191, s[42:43]
	v_pk_fma_f32 v[132:133], v[90:91], v[132:133], v[102:103]
	v_cndmask_b32_e32 v159, v183, v176, vcc
	v_pk_fma_f32 v[130:131], v[94:95], v[130:131], v[132:133]
	v_cndmask_b32_e32 v158, v178, v0, vcc
	v_pk_fma_f32 v[130:131], v[156:157], v[98:99], v[130:131]
	v_cndmask_b32_e64 v157, v177, v185, s[42:43]
	v_cndmask_b32_e64 v156, v107, v179, s[42:43]
	v_pk_fma_f32 v[158:159], v[92:93], v[158:159], v[104:105]
	v_cndmask_b32_e32 v171, v187, v196, vcc
	v_cndmask_b32_e32 v170, v181, v192, vcc
	v_pk_fma_f32 v[156:157], v[96:97], v[156:157], v[158:159]
	v_cndmask_b32_e64 v159, v197, v189, s[42:43]
	v_cndmask_b32_e64 v158, v193, v184, s[42:43]
	v_pk_fma_f32 v[90:91], v[90:91], v[170:171], v[102:103]
	v_cndmask_b32_e32 v103, v176, v186, vcc
	v_pk_fma_f32 v[90:91], v[94:95], v[158:159], v[90:91]
	v_cndmask_b32_e32 v102, v0, v180, vcc
	v_pk_fma_f32 v[90:91], v[122:123], v[98:99], v[90:91]
	v_cndmask_b32_e64 v99, v188, v177, s[42:43]
	v_cndmask_b32_e64 v98, v182, v107, s[42:43]
	v_pk_fma_f32 v[92:93], v[92:93], v[102:103], v[104:105]
	v_pk_fma_f32 v[92:93], v[96:97], v[98:99], v[92:93]
	v_mov_b32_e32 v125, v124
	v_pk_fma_f32 v[92:93], v[120:121], v[100:101], v[92:93]
	v_mov_b32_e32 v129, v128
	v_mov_b32_e32 v98, v124
	v_mov_b32_e32 v99, v124
	v_pk_mul_f32 v[72:73], v[72:73], v[98:99]
	v_pk_mul_f32 v[70:71], v[70:71], v[124:125]
	v_pk_mul_f32 v[66:67], v[66:67], v[128:129]
	s_nop 1
	v_mov_b32_e32 v98, v128
	v_mov_b32_e32 v99, v128
	s_nop 1
	v_mov_b32_dpp v123, v70 row_ror:2 row_mask:0xf bank_mask:0xf
	s_nop 1
	v_mov_b32_dpp v125, v71 row_ror:2 row_mask:0xf bank_mask:0xf
	s_nop 1
	v_mov_b32_dpp v129, v72 row_ror:2 row_mask:0xf bank_mask:0xf
	s_nop 1
	v_mov_b32_dpp v159, v73 row_ror:2 row_mask:0xf bank_mask:0xf
	v_pk_fma_f32 v[134:135], v[134:135], v[100:101], v[156:157]
	v_pk_mul_f32 v[68:69], v[68:69], v[98:99]
	v_mov_b32_dpp v122, v70 row_ror:1 row_mask:0xf bank_mask:0xf
	v_mov_b32_dpp v124, v71 row_ror:1 row_mask:0xf bank_mask:0xf
	v_mov_b32_dpp v128, v72 row_ror:1 row_mask:0xf bank_mask:0xf
	v_mov_b32_dpp v158, v73 row_ror:1 row_mask:0xf bank_mask:0xf
	v_cndmask_b32_e32 v98, v152, v123, vcc
	v_cndmask_b32_e32 v99, v153, v125, vcc
	v_cndmask_b32_e32 v100, v154, v129, vcc
	v_cndmask_b32_e32 v101, v155, v159, vcc
	v_cndmask_b32_e64 v102, v122, v136, s[42:43]
	v_cndmask_b32_e64 v103, v124, v137, s[42:43]
	v_cndmask_b32_e64 v104, v128, v150, s[42:43]
	v_cndmask_b32_e64 v105, v158, v151, s[42:43]
	s_waitcnt vmcnt(1)
	v_pk_fma_f32 v[100:101], v[84:85], v[100:101], v[88:89]
	v_pk_fma_f32 v[98:99], v[82:83], v[98:99], v[86:87]
	v_pk_fma_f32 v[100:101], v[80:81], v[104:105], v[100:101]
	v_pk_fma_f32 v[98:99], v[78:79], v[102:103], v[98:99]
	v_add_u32_e32 v0, 0x90, v106
	v_add_u32_e32 v120, 0xa0, v106
	v_add_u32_e32 v121, 0xb0, v106
	v_pk_mul_f32 v[114:115], v[112:113], s[98:99] op_sel_hi:[1,0]
	v_pk_mul_f32 v[118:119], v[116:117], s[98:99] op_sel_hi:[1,0]
	v_exp_f32_e32 v114, v114
	v_exp_f32_e32 v115, v115
	v_exp_f32_e32 v118, v118
	v_exp_f32_e32 v119, v119
	v_pk_add_f32 v[114:115], v[114:115], 1.0 op_sel_hi:[1,0]
	v_pk_add_f32 v[118:119], v[118:119], 1.0 op_sel_hi:[1,0]
	v_rcp_f32_e32 v114, v114
	v_rcp_f32_e32 v115, v115
	v_rcp_f32_e32 v118, v118
	v_rcp_f32_e32 v119, v119
	v_pk_mul_f32 v[106:107], v[112:113], v[114:115]
	v_pk_mul_f32 v[112:113], v[116:117], v[118:119]
	v_pk_fma_f32 v[72:73], v[72:73], v[76:77], v[100:101]
	v_pk_fma_f32 v[70:71], v[70:71], v[74:75], v[98:99]
	v_pk_mul_f32 v[72:73], v[112:113], v[72:73]
	v_pk_mul_f32 v[70:71], v[106:107], v[70:71]
	v_cvt_pk_bf16_f32 v230, v70, v71
	v_cvt_pk_bf16_f32 v231, v72, v73
	s_nop 1
	s_nop 1
	v_mov_b32_dpp v114, v66 row_ror:2 row_mask:0xf bank_mask:0xf
	s_nop 1
	v_mov_b32_dpp v116, v67 row_ror:2 row_mask:0xf bank_mask:0xf
	s_nop 1
	v_mov_b32_dpp v118, v68 row_ror:2 row_mask:0xf bank_mask:0xf
	s_nop 1
	v_mov_b32_dpp v126, v69 row_ror:2 row_mask:0xf bank_mask:0xf
	v_mov_b32_dpp v0, v66 row_ror:1 row_mask:0xf bank_mask:0xf
	v_mov_b32_dpp v115, v67 row_ror:1 row_mask:0xf bank_mask:0xf
	v_mov_b32_dpp v117, v68 row_ror:1 row_mask:0xf bank_mask:0xf
	v_mov_b32_dpp v119, v69 row_ror:1 row_mask:0xf bank_mask:0xf
	v_cndmask_b32_e32 v70, v123, v114, vcc
	v_cndmask_b32_e32 v71, v125, v116, vcc
	v_cndmask_b32_e32 v98, v129, v118, vcc
	v_cndmask_b32_e32 v99, v159, v126, vcc
	v_cndmask_b32_e64 v102, v0, v122, s[42:43]
	v_cndmask_b32_e64 v103, v115, v124, s[42:43]
	v_cndmask_b32_e64 v104, v117, v128, s[42:43]
	v_cndmask_b32_e64 v105, v119, v158, s[42:43]
	v_pk_fma_f32 v[98:99], v[84:85], v[98:99], v[88:89]
	v_pk_fma_f32 v[70:71], v[82:83], v[70:71], v[86:87]
	v_pk_fma_f32 v[98:99], v[80:81], v[104:105], v[98:99]
	v_pk_fma_f32 v[70:71], v[78:79], v[102:103], v[70:71]
	v_pk_mul_f32 v[132:133], v[130:131], s[98:99] op_sel_hi:[1,0]
	v_pk_mul_f32 v[156:157], v[134:135], s[98:99] op_sel_hi:[1,0]
	v_exp_f32_e32 v132, v132
	v_exp_f32_e32 v133, v133
	v_exp_f32_e32 v156, v156
	v_exp_f32_e32 v157, v157
	v_pk_add_f32 v[132:133], v[132:133], 1.0 op_sel_hi:[1,0]
	v_pk_add_f32 v[156:157], v[156:157], 1.0 op_sel_hi:[1,0]
	v_rcp_f32_e32 v132, v132
	v_rcp_f32_e32 v133, v133
	v_rcp_f32_e32 v156, v156
	v_rcp_f32_e32 v157, v157
	v_pk_mul_f32 v[106:107], v[130:131], v[132:133]
	v_pk_mul_f32 v[112:113], v[134:135], v[156:157]
	v_pk_fma_f32 v[68:69], v[68:69], v[76:77], v[98:99]
	v_pk_fma_f32 v[66:67], v[66:67], v[74:75], v[70:71]
	v_pk_mul_f32 v[68:69], v[112:113], v[68:69]
	v_pk_mul_f32 v[66:67], v[106:107], v[66:67]
	v_cvt_pk_bf16_f32 v232, v66, v67
	v_cvt_pk_bf16_f32 v233, v68, v69
	s_nop 1
	s_nop 1
	v_mov_b32_dpp v66, v110 row_ror:2 row_mask:0xf bank_mask:0xf
	s_nop 1
	v_mov_b32_dpp v67, v111 row_ror:2 row_mask:0xf bank_mask:0xf
	s_nop 1
	v_mov_b32_dpp v68, v108 row_ror:2 row_mask:0xf bank_mask:0xf
	s_nop 1
	v_mov_b32_dpp v69, v109 row_ror:2 row_mask:0xf bank_mask:0xf
	v_mov_b32_dpp v70, v110 row_ror:1 row_mask:0xf bank_mask:0xf
	v_mov_b32_dpp v71, v111 row_ror:1 row_mask:0xf bank_mask:0xf
	v_mov_b32_dpp v98, v108 row_ror:1 row_mask:0xf bank_mask:0xf
	v_mov_b32_dpp v99, v109 row_ror:1 row_mask:0xf bank_mask:0xf
	v_cndmask_b32_e32 v66, v114, v66, vcc
	v_cndmask_b32_e32 v67, v116, v67, vcc
	v_cndmask_b32_e32 v68, v118, v68, vcc
	v_cndmask_b32_e32 v69, v126, v69, vcc
	v_cndmask_b32_e64 v70, v70, v0, s[42:43]
	v_cndmask_b32_e64 v71, v71, v115, s[42:43]
	v_cndmask_b32_e64 v98, v98, v117, s[42:43]
	v_cndmask_b32_e64 v99, v99, v119, s[42:43]
	v_pk_fma_f32 v[66:67], v[82:83], v[66:67], v[86:87]
	v_pk_fma_f32 v[68:69], v[84:85], v[68:69], v[88:89]
	v_pk_fma_f32 v[66:67], v[78:79], v[70:71], v[66:67]
	v_pk_fma_f32 v[68:69], v[80:81], v[98:99], v[68:69]
	v_pk_mul_f32 v[94:95], v[90:91], s[98:99] op_sel_hi:[1,0]
	v_pk_mul_f32 v[96:97], v[92:93], s[98:99] op_sel_hi:[1,0]
	v_exp_f32_e32 v94, v94
	v_exp_f32_e32 v95, v95
	v_exp_f32_e32 v96, v96
	v_exp_f32_e32 v97, v97
	v_pk_add_f32 v[94:95], v[94:95], 1.0 op_sel_hi:[1,0]
	v_pk_add_f32 v[96:97], v[96:97], 1.0 op_sel_hi:[1,0]
	v_rcp_f32_e32 v94, v94
	v_rcp_f32_e32 v95, v95
	v_rcp_f32_e32 v96, v96
	v_rcp_f32_e32 v97, v97
	v_pk_mul_f32 v[90:91], v[90:91], v[94:95]
	v_pk_mul_f32 v[92:93], v[92:93], v[96:97]
	v_pk_fma_f32 v[66:67], v[110:111], v[74:75], v[66:67]
	v_pk_fma_f32 v[68:69], v[108:109], v[76:77], v[68:69]
	v_pk_mul_f32 v[66:67], v[90:91], v[66:67]
	v_pk_mul_f32 v[68:69], v[92:93], v[68:69]
	v_cvt_pk_bf16_f32 v234, v66, v67
	s_nop 0
	v_cvt_pk_bf16_f32 v235, v68, v69
	s_nop 0
	v_and_b32_e32 v97, 15, v226
	v_or_b32_e32 v74, s4, v97
	v_ashrrev_i32_e32 v75, 31, v74
	v_lshl_add_u64 v[72:73], v[74:75], 3, s[38:39]
	global_load_dwordx2 v[76:77], v[72:73], off
	global_load_dwordx2 v[70:71], v[72:73], off offset:128
	global_load_dwordx2 v[68:69], v[72:73], off offset:256
	s_nop 0
	global_load_dwordx2 v[72:73], v[72:73], off offset:384
	v_ashrrev_i32_e32 v0, 1, v226
	v_and_b32_e32 v0, -8, v0
	v_add_u32_e32 v66, s21, v0
	s_waitcnt vmcnt(3)
	v_ffbh_u32_e32 v0, v77
	v_min_u32_e32 v0, 32, v0
	v_lshlrev_b64 v[76:77], v0, v[76:77]
	v_min_u32_e32 v67, 1, v76
	v_or_b32_e32 v67, v77, v67
	v_cvt_f32_u32_e32 v67, v67
	v_sub_u32_e32 v0, 32, v0
	v_ldexp_f32 v0, v67, v0
	v_fmamk_f32 v0, v0, 0x2e800000, v210
	s_nop 0
	v_rsq_f32_e32 v0, v0
	s_nop 0
	s_nop 0
	v_ashrrev_i32_e32 v67, 31, v66
	v_pk_mul_f32 v[92:93], v[64:65], v[0:1] op_sel_hi:[1,0]
	v_pk_mul_f32 v[90:91], v[62:63], v[0:1] op_sel_hi:[1,0]
	v_pk_mul_f32 v[86:87], v[60:61], v[0:1] op_sel_hi:[1,0]
	v_pk_mul_f32 v[88:89], v[58:59], v[0:1] op_sel_hi:[1,0]
	v_lshl_add_u64 v[58:59], v[66:67], 1, s[76:77]
	v_cmp_gt_u32_e32 vcc, 2, v97
	s_and_saveexec_b64 s[0:1], vcc
	s_cbranch_execz .LBB0_123
	v_mul_u32_u24_e32 v0, 0x1600, v97
	v_lshlrev_b32_e32 v0, 1, v0
	v_cvt_pk_bf16_f32 v60, v90, v91
	v_cvt_pk_bf16_f32 v61, v92, v93
	v_lshl_add_u64 v[64:65], v[58:59], 0, v[0:1]
	v_cvt_pk_bf16_f32 v62, v88, v89
	v_cvt_pk_bf16_f32 v63, v86, v87
	global_store_dwordx2 v[64:65], v[60:61], off offset:8
	global_store_dwordx2 v[64:65], v[62:63], off offset:264

.LBB0_125:
	s_or_b64 exec, exec, s[0:1]
	v_ffbh_u32_e32 v0, v71
	v_min_u32_e32 v0, 32, v0
	v_lshlrev_b64 v[50:51], v0, v[70:71]
	v_min_u32_e32 v50, 1, v50
	v_or_b32_e32 v50, v51, v50
	v_cvt_f32_u32_e32 v50, v50
	v_sub_u32_e32 v0, 32, v0
	s_or_b32 s5, s5, 4
	v_add_u32_e32 v94, s5, v66
	v_ldexp_f32 v0, v50, v0
	v_fmamk_f32 v0, v0, 0x2e800000, v210
	s_nop 0
	v_rsq_f32_e32 v0, v0
	s_nop 0
	s_nop 0
	v_mov_b32_e32 v84, v0
	v_ffbh_u32_e32 v0, v69
	v_min_u32_e32 v0, 32, v0
	v_pk_mul_f32 v[100:101], v[46:47], v[84:85] op_sel_hi:[1,0]
	v_lshlrev_b64 v[46:47], v0, v[68:69]
	v_min_u32_e32 v46, 1, v46
	v_or_b32_e32 v46, v47, v46
	v_cvt_f32_u32_e32 v46, v46
	v_sub_u32_e32 v0, 32, v0
	v_pk_mul_f32 v[98:99], v[48:49], v[84:85] op_sel_hi:[1,0]
	v_ldexp_f32 v0, v46, v0
	v_fmamk_f32 v0, v0, 0x2e800000, v210
	s_nop 0
	v_rsq_f32_e32 v0, v0
	s_nop 0
	s_nop 0
	v_mov_b32_e32 v96, v0
	v_pk_mul_f32 v[102:103], v[44:45], v[96:97] op_sel_hi:[1,0]
	v_pk_mul_f32 v[112:113], v[42:43], v[96:97] op_sel_hi:[1,0]
	v_ashrrev_i32_e32 v95, 31, v94
	v_lshlrev_b64 v[54:55], 2, v[94:95]
	v_lshl_add_u64 v[42:43], s[44:45], 0, v[54:55]
	v_lshl_add_u64 v[44:45], s[60:61], 0, v[54:55]
	global_load_dwordx4 v[58:61], v[42:43], off
	global_load_dwordx4 v[62:65], v[44:45], off
	v_lshl_add_u64 v[42:43], s[2:3], 0, v[54:55]
	global_load_dwordx4 v[66:69], v[42:43], off
	v_lshl_add_u64 v[42:43], s[48:49], 0, v[54:55]
	global_load_dwordx4 v[70:73], v[42:43], off
	s_nop 1
	v_cmp_lt_u32_e32 vcc, 1, v97
	v_mov_b32_dpp v120, v90 row_ror:1 row_mask:0xf bank_mask:0xf
	v_mov_b32_dpp v118, v90 row_ror:2 row_mask:0xf bank_mask:0xf
	v_mov_b32_dpp v121, v91 row_ror:1 row_mask:0xf bank_mask:0xf
	v_mov_b32_dpp v119, v91 row_ror:2 row_mask:0xf bank_mask:0xf
	v_mov_b32_dpp v116, v92 row_ror:1 row_mask:0xf bank_mask:0xf
	v_mov_b32_dpp v114, v92 row_ror:2 row_mask:0xf bank_mask:0xf
	v_mov_b32_dpp v117, v93 row_ror:1 row_mask:0xf bank_mask:0xf
	v_mov_b32_dpp v115, v93 row_ror:2 row_mask:0xf bank_mask:0xf
	v_mov_b32_dpp v137, v100 row_ror:1 row_mask:0xf bank_mask:0xf
	v_mov_b32_dpp v136, v100 row_ror:2 row_mask:0xf bank_mask:0xf
	v_mov_b32_dpp v153, v101 row_ror:1 row_mask:0xf bank_mask:0xf
	v_mov_b32_dpp v152, v101 row_ror:2 row_mask:0xf bank_mask:0xf
	v_mov_b32_dpp v125, v98 row_ror:1 row_mask:0xf bank_mask:0xf
	v_mov_b32_dpp v124, v98 row_ror:2 row_mask:0xf bank_mask:0xf
	v_mov_b32_dpp v131, v99 row_ror:1 row_mask:0xf bank_mask:0xf
	v_mov_b32_dpp v129, v99 row_ror:2 row_mask:0xf bank_mask:0xf
	v_mov_b32_dpp v130, v112 row_ror:1 row_mask:0xf bank_mask:0xf
	v_mov_b32_dpp v127, v112 row_ror:2 row_mask:0xf bank_mask:0xf
	v_mov_b32_dpp v135, v113 row_ror:1 row_mask:0xf bank_mask:0xf
	v_mov_b32_dpp v133, v113 row_ror:2 row_mask:0xf bank_mask:0xf
	v_mov_b32_dpp v75, v102 row_ror:1 row_mask:0xf bank_mask:0xf
	v_mov_b32_dpp v0, v102 row_ror:2 row_mask:0xf bank_mask:0xf
	v_mov_b32_dpp v123, v103 row_ror:1 row_mask:0xf bank_mask:0xf
	v_mov_b32_dpp v122, v103 row_ror:2 row_mask:0xf bank_mask:0xf
	v_mov_b32_dpp v151, v82 row_ror:1 row_mask:0xf bank_mask:0xf
	v_mov_b32_dpp v150, v82 row_ror:2 row_mask:0xf bank_mask:0xf
	v_mov_b32_dpp v155, v83 row_ror:1 row_mask:0xf bank_mask:0xf
	v_mov_b32_dpp v154, v83 row_ror:2 row_mask:0xf bank_mask:0xf
	v_mov_b32_dpp v128, v80 row_ror:1 row_mask:0xf bank_mask:0xf
	v_mov_b32_dpp v126, v80 row_ror:2 row_mask:0xf bank_mask:0xf
	v_mov_b32_dpp v134, v81 row_ror:1 row_mask:0xf bank_mask:0xf
	v_mov_b32_dpp v132, v81 row_ror:2 row_mask:0xf bank_mask:0xf
	v_lshl_add_u64 v[42:43], s[96:97], 0, v[54:55]
	v_lshl_add_u64 v[44:45], s[62:63], 0, v[54:55]
	global_load_dwordx4 v[50:53], v[42:43], off
	global_load_dwordx4 v[46:49], v[44:45], off
	v_lshl_add_u64 v[42:43], s[64:65], 0, v[54:55]
	v_lshl_add_u64 v[54:55], s[66:67], 0, v[54:55]
	global_load_dwordx4 v[42:45], v[42:43], off
	s_nop 1
	global_load_dwordx4 v[54:57], v[54:55], off
	s_nop 1
	v_mov_b32_dpp v104, v88 row_ror:1 row_mask:0xf bank_mask:0xf
	v_mov_b32_dpp v108, v88 row_ror:2 row_mask:0xf bank_mask:0xf
	v_mov_b32_dpp v105, v89 row_ror:1 row_mask:0xf bank_mask:0xf
	v_mov_b32_dpp v109, v89 row_ror:2 row_mask:0xf bank_mask:0xf
	v_mov_b32_dpp v106, v86 row_ror:1 row_mask:0xf bank_mask:0xf
	v_mov_b32_dpp v110, v86 row_ror:2 row_mask:0xf bank_mask:0xf
	v_mov_b32_dpp v107, v87 row_ror:1 row_mask:0xf bank_mask:0xf
	v_mov_b32_dpp v111, v87 row_ror:2 row_mask:0xf bank_mask:0xf
	s_and_saveexec_b64 s[0:1], vcc
	s_cbranch_execz .Lcg_skip2
	s_waitcnt vmcnt(4)
	v_pk_fma_f32 v[156:157], v[60:61], v[114:115], v[72:73]
	s_nop 0
	v_pk_fma_f32 v[156:157], v[64:65], v[116:117], v[156:157]
	s_nop 0
	v_pk_fma_f32 v[92:93], v[92:93], v[68:69], v[156:157]
	v_pk_fma_f32 v[156:157], v[58:59], v[118:119], v[70:71]
	v_pk_fma_f32 v[156:157], v[62:63], v[120:121], v[156:157]
	v_pk_fma_f32 v[90:91], v[90:91], v[66:67], v[156:157]
	v_pk_mul_f32 v[156:157], v[90:91], s[98:99] op_sel_hi:[1,0]
	v_pk_mul_f32 v[158:159], v[92:93], s[98:99] op_sel_hi:[1,0]
	v_exp_f32_e32 v156, v156
	v_exp_f32_e32 v157, v157
	v_exp_f32_e32 v158, v158
	v_exp_f32_e32 v159, v159
	v_pk_add_f32 v[156:157], v[156:157], 1.0 op_sel_hi:[1,0]
	v_pk_add_f32 v[158:159], v[158:159], 1.0 op_sel_hi:[1,0]
	v_rcp_f32_e32 v156, v156
	v_rcp_f32_e32 v157, v157
	v_rcp_f32_e32 v158, v158
	v_rcp_f32_e32 v159, v159
	v_pk_mul_f32 v[90:91], v[90:91], v[156:157]
	v_pk_mul_f32 v[92:93], v[92:93], v[158:159]
	s_waitcnt vmcnt(0)
	v_pk_fma_f32 v[156:157], v[52:53], v[110:111], v[56:57]
	v_pk_fma_f32 v[158:159], v[50:51], v[108:109], v[54:55]
	v_pk_fma_f32 v[156:157], v[48:49], v[106:107], v[156:157]
	v_pk_fma_f32 v[158:159], v[46:47], v[104:105], v[158:159]
	v_pk_fma_f32 v[86:87], v[86:87], v[44:45], v[156:157]
	v_pk_fma_f32 v[88:89], v[88:89], v[42:43], v[158:159]
	v_pk_mul_f32 v[86:87], v[92:93], v[86:87]
	v_pk_mul_f32 v[88:89], v[90:91], v[88:89]
	s_nop 0
	v_cvt_pk_bf16_f32 v238, v88, v89
	v_cvt_pk_bf16_f32 v239, v86, v87
	v_mov_b64_e32 v[86:87], s[36:37]
	v_mad_i64_i32 v[86:87], s[6:7], v74, s46, v[86:87]
	v_lshl_add_u64 v[86:87], v[94:95], 1, v[86:87]
	v_mov_b32_e32 v236, v248
	v_mov_b32_e32 v237, v249
	global_store_dwordx4 v[86:87], v[236:239], off offset:-8
.LBB0_127:
	s_or_b64 exec, exec, s[0:1]
	v_cmp_eq_u32_e64 s[42:43], 0, v97
	v_cndmask_b32_e32 v89, v119, v152, vcc
	v_cndmask_b32_e32 v88, v118, v136, vcc
	v_cndmask_b32_e64 v87, v153, v121, s[42:43]
	v_cndmask_b32_e64 v86, v137, v120, s[42:43]
	s_waitcnt vmcnt(4)
	v_pk_fma_f32 v[88:89], v[58:59], v[88:89], v[70:71]
	v_cndmask_b32_e32 v93, v115, v129, vcc
	v_cndmask_b32_e32 v92, v114, v124, vcc
	v_pk_fma_f32 v[86:87], v[62:63], v[86:87], v[88:89]
	v_cndmask_b32_e64 v91, v131, v117, s[42:43]
	v_cndmask_b32_e64 v90, v125, v116, s[42:43]
	v_pk_fma_f32 v[92:93], v[60:61], v[92:93], v[72:73]
	v_pk_fma_f32 v[86:87], v[100:101], v[66:67], v[86:87]
	v_pk_fma_f32 v[90:91], v[64:65], v[90:91], v[92:93]
	v_cndmask_b32_e32 v101, v152, v133, vcc
	v_cndmask_b32_e32 v100, v136, v127, vcc
	v_pk_fma_f32 v[90:91], v[98:99], v[68:69], v[90:91]
	v_cndmask_b32_e64 v99, v135, v153, s[42:43]
	v_cndmask_b32_e64 v98, v130, v137, s[42:43]
	v_pk_fma_f32 v[100:101], v[58:59], v[100:101], v[70:71]
	v_cndmask_b32_e32 v115, v129, v122, vcc
	v_pk_fma_f32 v[98:99], v[62:63], v[98:99], v[100:101]
	v_cndmask_b32_e32 v114, v124, v0, vcc
	v_pk_fma_f32 v[98:99], v[112:113], v[66:67], v[98:99]
	v_cndmask_b32_e64 v113, v123, v131, s[42:43]
	v_cndmask_b32_e64 v112, v75, v125, s[42:43]
	v_pk_fma_f32 v[114:115], v[60:61], v[114:115], v[72:73]
	v_cndmask_b32_e32 v117, v133, v154, vcc
	v_cndmask_b32_e32 v116, v127, v150, vcc
	v_pk_fma_f32 v[112:113], v[64:65], v[112:113], v[114:115]
	v_cndmask_b32_e64 v115, v155, v135, s[42:43]
	v_cndmask_b32_e64 v114, v151, v130, s[42:43]
	v_pk_fma_f32 v[58:59], v[58:59], v[116:117], v[70:71]
	v_cndmask_b32_e32 v71, v122, v132, vcc
	v_pk_fma_f32 v[58:59], v[62:63], v[114:115], v[58:59]
	v_cndmask_b32_e32 v70, v0, v126, vcc
	v_pk_fma_f32 v[58:59], v[82:83], v[66:67], v[58:59]
	v_cndmask_b32_e64 v67, v134, v123, s[42:43]
	v_cndmask_b32_e64 v66, v128, v75, s[42:43]
	v_pk_fma_f32 v[60:61], v[60:61], v[70:71], v[72:73]
	v_pk_fma_f32 v[60:61], v[64:65], v[66:67], v[60:61]
	v_mov_b32_e32 v85, v84
	v_pk_fma_f32 v[60:61], v[80:81], v[68:69], v[60:61]
	v_mov_b32_e32 v97, v96
	v_mov_b32_e32 v66, v84
	v_mov_b32_e32 v67, v84
	v_pk_mul_f32 v[40:41], v[40:41], v[66:67]
	v_pk_mul_f32 v[38:39], v[38:39], v[84:85]
	v_pk_mul_f32 v[34:35], v[34:35], v[96:97]
	s_nop 1
	v_mov_b32_e32 v66, v96
	v_mov_b32_e32 v67, v96
	s_nop 1
	v_mov_b32_dpp v85, v38 row_ror:2 row_mask:0xf bank_mask:0xf
	s_nop 1
	v_mov_b32_dpp v97, v39 row_ror:2 row_mask:0xf bank_mask:0xf
	s_nop 1
	v_mov_b32_dpp v115, v40 row_ror:2 row_mask:0xf bank_mask:0xf
	s_nop 1
	v_mov_b32_dpp v117, v41 row_ror:2 row_mask:0xf bank_mask:0xf
	v_pk_fma_f32 v[102:103], v[102:103], v[68:69], v[112:113]
	v_pk_mul_f32 v[36:37], v[36:37], v[66:67]
	v_mov_b32_dpp v84, v38 row_ror:1 row_mask:0xf bank_mask:0xf
	v_mov_b32_dpp v96, v39 row_ror:1 row_mask:0xf bank_mask:0xf
	v_mov_b32_dpp v114, v40 row_ror:1 row_mask:0xf bank_mask:0xf
	v_mov_b32_dpp v116, v41 row_ror:1 row_mask:0xf bank_mask:0xf
	v_cndmask_b32_e32 v66, v108, v85, vcc
	v_cndmask_b32_e32 v67, v109, v97, vcc
	v_cndmask_b32_e32 v68, v110, v115, vcc
	v_cndmask_b32_e32 v69, v111, v117, vcc
	v_cndmask_b32_e64 v70, v84, v104, s[42:43]
	v_cndmask_b32_e64 v71, v96, v105, s[42:43]
	v_cndmask_b32_e64 v72, v114, v106, s[42:43]
	v_cndmask_b32_e64 v73, v116, v107, s[42:43]
	s_waitcnt vmcnt(1)
	v_pk_fma_f32 v[68:69], v[52:53], v[68:69], v[56:57]
	v_pk_fma_f32 v[66:67], v[50:51], v[66:67], v[54:55]
	v_pk_fma_f32 v[68:69], v[48:49], v[72:73], v[68:69]
	v_pk_fma_f32 v[66:67], v[46:47], v[70:71], v[66:67]
	v_or_b32_e32 v0, 16, v74
	v_or_b32_e32 v82, 32, v74
	v_or_b32_e32 v83, 48, v74
	v_pk_mul_f32 v[88:89], v[86:87], s[98:99] op_sel_hi:[1,0]
	v_pk_mul_f32 v[92:93], v[90:91], s[98:99] op_sel_hi:[1,0]
	v_exp_f32_e32 v88, v88
	v_exp_f32_e32 v89, v89
	v_exp_f32_e32 v92, v92
	v_exp_f32_e32 v93, v93
	v_pk_add_f32 v[88:89], v[88:89], 1.0 op_sel_hi:[1,0]
	v_pk_add_f32 v[92:93], v[92:93], 1.0 op_sel_hi:[1,0]
	v_rcp_f32_e32 v88, v88
	v_rcp_f32_e32 v89, v89
	v_rcp_f32_e32 v92, v92
	v_rcp_f32_e32 v93, v93
	v_pk_mul_f32 v[74:75], v[86:87], v[88:89]
	v_pk_mul_f32 v[80:81], v[90:91], v[92:93]
	v_pk_fma_f32 v[40:41], v[40:41], v[44:45], v[68:69]
	v_pk_fma_f32 v[38:39], v[38:39], v[42:43], v[66:67]
	v_pk_mul_f32 v[40:41], v[80:81], v[40:41]
	v_pk_mul_f32 v[38:39], v[74:75], v[38:39]
	v_cvt_pk_bf16_f32 v238, v38, v39
	v_cvt_pk_bf16_f32 v239, v40, v41
	v_mov_b64_e32 v[40:41], s[36:37]
	v_mad_i64_i32 v[66:67], s[0:1], v0, s46, v[40:41]
	v_lshlrev_b64 v[68:69], 1, v[94:95]
	s_nop 1
	v_lshl_add_u64 v[66:67], v[66:67], 0, v[68:69]
	s_nop 1
	v_mov_b32_dpp v86, v34 row_ror:2 row_mask:0xf bank_mask:0xf
	s_nop 1
	v_mov_b32_dpp v88, v35 row_ror:2 row_mask:0xf bank_mask:0xf
	s_nop 1
	v_mov_b32_dpp v90, v36 row_ror:2 row_mask:0xf bank_mask:0xf
	s_nop 1
	v_mov_b32_dpp v92, v37 row_ror:2 row_mask:0xf bank_mask:0xf
	v_mov_b32_e32 v236, v250
	v_mov_b32_e32 v237, v251
	global_store_dwordx4 v[66:67], v[236:239], off offset:-8
	v_mov_b32_dpp v0, v34 row_ror:1 row_mask:0xf bank_mask:0xf
	v_mov_b32_dpp v87, v35 row_ror:1 row_mask:0xf bank_mask:0xf
	v_mov_b32_dpp v89, v36 row_ror:1 row_mask:0xf bank_mask:0xf
	v_mov_b32_dpp v91, v37 row_ror:1 row_mask:0xf bank_mask:0xf
	v_cndmask_b32_e32 v38, v85, v86, vcc
	v_cndmask_b32_e32 v39, v97, v88, vcc
	v_cndmask_b32_e32 v66, v115, v90, vcc
	v_cndmask_b32_e32 v67, v117, v92, vcc
	v_cndmask_b32_e64 v70, v0, v84, s[42:43]
	v_cndmask_b32_e64 v71, v87, v96, s[42:43]
	v_cndmask_b32_e64 v72, v89, v114, s[42:43]
	v_cndmask_b32_e64 v73, v91, v116, s[42:43]
	v_pk_fma_f32 v[66:67], v[52:53], v[66:67], v[56:57]
	v_pk_fma_f32 v[38:39], v[50:51], v[38:39], v[54:55]
	v_pk_fma_f32 v[66:67], v[48:49], v[72:73], v[66:67]
	v_pk_fma_f32 v[38:39], v[46:47], v[70:71], v[38:39]
	v_pk_mul_f32 v[100:101], v[98:99], s[98:99] op_sel_hi:[1,0]
	v_pk_mul_f32 v[112:113], v[102:103], s[98:99] op_sel_hi:[1,0]
	v_exp_f32_e32 v100, v100
	v_exp_f32_e32 v101, v101
	v_exp_f32_e32 v112, v112
	v_exp_f32_e32 v113, v113
	v_pk_add_f32 v[100:101], v[100:101], 1.0 op_sel_hi:[1,0]
	v_pk_add_f32 v[112:113], v[112:113], 1.0 op_sel_hi:[1,0]
	v_rcp_f32_e32 v100, v100
	v_rcp_f32_e32 v101, v101
	v_rcp_f32_e32 v112, v112
	v_rcp_f32_e32 v113, v113
	v_pk_mul_f32 v[74:75], v[98:99], v[100:101]
	v_pk_mul_f32 v[80:81], v[102:103], v[112:113]
	v_pk_fma_f32 v[36:37], v[36:37], v[44:45], v[66:67]
	v_pk_fma_f32 v[34:35], v[34:35], v[42:43], v[38:39]
	v_pk_mul_f32 v[36:37], v[80:81], v[36:37]
	v_pk_mul_f32 v[34:35], v[74:75], v[34:35]
	v_cvt_pk_bf16_f32 v238, v34, v35
	v_cvt_pk_bf16_f32 v239, v36, v37
	v_mad_i64_i32 v[36:37], s[0:1], v82, s46, v[40:41]
	v_lshl_add_u64 v[36:37], v[36:37], 0, v[68:69]
	v_mov_b32_e32 v236, v244
	v_mov_b32_e32 v237, v245
	global_store_dwordx4 v[36:37], v[236:239], off offset:-8
	s_nop 1
	s_nop 1
	v_mov_b32_dpp v34, v78 row_ror:2 row_mask:0xf bank_mask:0xf
	s_nop 1
	v_mov_b32_dpp v35, v79 row_ror:2 row_mask:0xf bank_mask:0xf
	s_nop 1
	v_mov_b32_dpp v36, v76 row_ror:2 row_mask:0xf bank_mask:0xf
	s_nop 1
	v_mov_b32_dpp v37, v77 row_ror:2 row_mask:0xf bank_mask:0xf
	v_mov_b32_dpp v38, v78 row_ror:1 row_mask:0xf bank_mask:0xf
	v_mov_b32_dpp v39, v79 row_ror:1 row_mask:0xf bank_mask:0xf
	v_mov_b32_dpp v66, v76 row_ror:1 row_mask:0xf bank_mask:0xf
	v_mov_b32_dpp v67, v77 row_ror:1 row_mask:0xf bank_mask:0xf
	v_cndmask_b32_e32 v34, v86, v34, vcc
	v_cndmask_b32_e32 v35, v88, v35, vcc
	v_cndmask_b32_e32 v36, v90, v36, vcc
	v_cndmask_b32_e32 v37, v92, v37, vcc
	v_cndmask_b32_e64 v38, v38, v0, s[42:43]
	v_cndmask_b32_e64 v39, v39, v87, s[42:43]
	v_cndmask_b32_e64 v66, v66, v89, s[42:43]
	v_cndmask_b32_e64 v67, v67, v91, s[42:43]
	v_pk_fma_f32 v[34:35], v[50:51], v[34:35], v[54:55]
	v_pk_fma_f32 v[36:37], v[52:53], v[36:37], v[56:57]
	v_pk_fma_f32 v[34:35], v[46:47], v[38:39], v[34:35]
	v_pk_fma_f32 v[36:37], v[48:49], v[66:67], v[36:37]
	v_pk_mul_f32 v[62:63], v[58:59], s[98:99] op_sel_hi:[1,0]
	v_pk_mul_f32 v[64:65], v[60:61], s[98:99] op_sel_hi:[1,0]
	v_exp_f32_e32 v62, v62
	v_exp_f32_e32 v63, v63
	v_exp_f32_e32 v64, v64
	v_exp_f32_e32 v65, v65
	v_pk_add_f32 v[62:63], v[62:63], 1.0 op_sel_hi:[1,0]
	v_pk_add_f32 v[64:65], v[64:65], 1.0 op_sel_hi:[1,0]
	v_rcp_f32_e32 v62, v62
	v_rcp_f32_e32 v63, v63
	v_rcp_f32_e32 v64, v64
	v_rcp_f32_e32 v65, v65
	v_pk_mul_f32 v[58:59], v[58:59], v[62:63]
	v_pk_mul_f32 v[60:61], v[60:61], v[64:65]
	v_pk_fma_f32 v[34:35], v[78:79], v[42:43], v[34:35]
	v_pk_fma_f32 v[36:37], v[76:77], v[44:45], v[36:37]
	v_pk_mul_f32 v[34:35], v[58:59], v[34:35]
	v_pk_mul_f32 v[36:37], v[60:61], v[36:37]
	v_cvt_pk_bf16_f32 v238, v34, v35
	s_nop 0
	v_cvt_pk_bf16_f32 v239, v36, v37
	v_mad_i64_i32 v[36:37], s[0:1], v83, s46, v[40:41]
	v_lshl_add_u64 v[36:37], v[36:37], 0, v[68:69]
	v_mov_b32_e32 v236, v246
	v_mov_b32_e32 v237, v247
	global_store_dwordx4 v[36:37], v[236:239], off offset:-8
	s_nop 0
	v_and_b32_e32 v108, 15, v226
	v_or_b32_e32 v56, s4, v108
	v_ashrrev_i32_e32 v57, 31, v56
	v_lshl_add_u64 v[40:41], v[56:57], 3, s[38:39]
	global_load_dwordx2 v[42:43], v[40:41], off offset:1024
	global_load_dwordx2 v[38:39], v[40:41], off offset:1152
	global_load_dwordx2 v[36:37], v[40:41], off offset:1280
	s_nop 0
	global_load_dwordx2 v[40:41], v[40:41], off offset:1408
	v_ashrrev_i32_e32 v0, 1, v226
	v_and_b32_e32 v0, -8, v0
	v_add_u32_e32 v34, s21, v0
	s_waitcnt vmcnt(3)
	v_ffbh_u32_e32 v0, v43
	v_min_u32_e32 v0, 32, v0
	v_lshlrev_b64 v[42:43], v0, v[42:43]
	v_min_u32_e32 v35, 1, v42
	v_or_b32_e32 v35, v43, v35
	v_cvt_f32_u32_e32 v35, v35
	v_sub_u32_e32 v0, 32, v0
	v_ldexp_f32 v0, v35, v0
	v_fmamk_f32 v0, v0, 0x2e800000, v210
	s_nop 0
	v_rsq_f32_e32 v0, v0
	s_nop 0
	s_nop 0
	v_ashrrev_i32_e32 v35, 31, v34
	v_pk_mul_f32 v[84:85], v[32:33], v[0:1] op_sel_hi:[1,0]
	v_pk_mul_f32 v[44:45], v[30:31], v[0:1] op_sel_hi:[1,0]
	v_pk_mul_f32 v[72:73], v[28:29], v[0:1] op_sel_hi:[1,0]
	v_pk_mul_f32 v[42:43], v[26:27], v[0:1] op_sel_hi:[1,0]
	v_lshl_add_u64 v[26:27], v[34:35], 1, s[78:79]
	v_cmp_gt_u32_e32 vcc, 2, v108
	s_and_saveexec_b64 s[0:1], vcc
	s_cbranch_execz .LBB0_129
	v_mul_u32_u24_e32 v0, 0x1600, v108
	v_lshlrev_b32_e32 v0, 1, v0
	v_cvt_pk_bf16_f32 v28, v44, v45
	v_cvt_pk_bf16_f32 v29, v84, v85
	v_lshl_add_u64 v[32:33], v[26:27], 0, v[0:1]
	v_cvt_pk_bf16_f32 v30, v42, v43
	v_cvt_pk_bf16_f32 v31, v72, v73
	global_store_dwordx2 v[32:33], v[28:29], off offset:8
	global_store_dwordx2 v[32:33], v[30:31], off offset:264

.LBB0_131:
	s_or_b64 exec, exec, s[0:1]
	v_ffbh_u32_e32 v0, v39
	v_min_u32_e32 v0, 32, v0
	v_lshlrev_b64 v[14:15], v0, v[38:39]
	v_min_u32_e32 v14, 1, v14
	v_or_b32_e32 v14, v15, v14
	v_cvt_f32_u32_e32 v14, v14
	v_sub_u32_e32 v0, 32, v0
	v_add_u32_e32 v58, s5, v34
	v_ldexp_f32 v0, v14, v0
	v_fmamk_f32 v0, v0, 0x2e800000, v210
	s_nop 0
	v_rsq_f32_e32 v0, v0
	s_nop 0
	s_nop 0
	v_mov_b32_e32 v52, v0
	v_ffbh_u32_e32 v0, v37
	v_min_u32_e32 v0, 32, v0
	v_lshlrev_b64 v[14:15], v0, v[36:37]
	v_min_u32_e32 v14, 1, v14
	v_or_b32_e32 v14, v15, v14
	v_cvt_f32_u32_e32 v14, v14
	v_sub_u32_e32 v0, 32, v0
	v_pk_mul_f32 v[60:61], v[20:21], v[52:53] op_sel_hi:[1,0]
	v_pk_mul_f32 v[54:55], v[18:19], v[52:53] op_sel_hi:[1,0]
	v_ldexp_f32 v0, v14, v0
	v_fmamk_f32 v0, v0, 0x2e800000, v210
	s_nop 0
	v_rsq_f32_e32 v0, v0
	s_nop 0
	s_nop 0
	v_mov_b32_e32 v62, v0
	v_pk_mul_f32 v[88:89], v[12:13], v[62:63] op_sel_hi:[1,0]
	v_pk_mul_f32 v[82:83], v[10:11], v[62:63] op_sel_hi:[1,0]
	v_ashrrev_i32_e32 v59, 31, v58
	v_lshlrev_b64 v[22:23], 2, v[58:59]
	v_lshl_add_u64 v[10:11], s[44:45], 0, v[22:23]
	v_lshl_add_u64 v[12:13], s[60:61], 0, v[22:23]
	global_load_dwordx4 v[26:29], v[10:11], off
	global_load_dwordx4 v[30:33], v[12:13], off
	v_lshl_add_u64 v[10:11], s[2:3], 0, v[22:23]
	global_load_dwordx4 v[34:37], v[10:11], off
	v_lshl_add_u64 v[10:11], s[48:49], 0, v[22:23]
	global_load_dwordx4 v[38:41], v[10:11], off
	s_nop 1
	v_cmp_lt_u32_e32 vcc, 1, v108
	v_mov_b32_dpp v66, v44 row_ror:1 row_mask:0xf bank_mask:0xf
	v_mov_b32_dpp v87, v44 row_ror:2 row_mask:0xf bank_mask:0xf
	v_mov_b32_dpp v67, v45 row_ror:1 row_mask:0xf bank_mask:0xf
	v_mov_b32_dpp v86, v45 row_ror:2 row_mask:0xf bank_mask:0xf
	v_mov_b32_dpp v80, v84 row_ror:1 row_mask:0xf bank_mask:0xf
	v_mov_b32_dpp v91, v84 row_ror:2 row_mask:0xf bank_mask:0xf
	v_mov_b32_dpp v81, v85 row_ror:1 row_mask:0xf bank_mask:0xf
	v_mov_b32_dpp v90, v85 row_ror:2 row_mask:0xf bank_mask:0xf
	v_mov_b32_dpp v0, v54 row_ror:1 row_mask:0xf bank_mask:0xf
	v_mov_b32_dpp v97, v54 row_ror:2 row_mask:0xf bank_mask:0xf
	v_mov_b32_dpp v109, v55 row_ror:1 row_mask:0xf bank_mask:0xf
	v_mov_b32_dpp v96, v55 row_ror:2 row_mask:0xf bank_mask:0xf
	v_mov_b32_dpp v110, v60 row_ror:1 row_mask:0xf bank_mask:0xf
	v_mov_b32_dpp v99, v60 row_ror:2 row_mask:0xf bank_mask:0xf
	v_mov_b32_dpp v111, v61 row_ror:1 row_mask:0xf bank_mask:0xf
	v_mov_b32_dpp v98, v61 row_ror:2 row_mask:0xf bank_mask:0xf
	v_mov_b32_dpp v112, v82 row_ror:1 row_mask:0xf bank_mask:0xf
	v_mov_b32_dpp v93, v82 row_ror:2 row_mask:0xf bank_mask:0xf
	v_mov_b32_dpp v113, v83 row_ror:1 row_mask:0xf bank_mask:0xf
	v_mov_b32_dpp v92, v83 row_ror:2 row_mask:0xf bank_mask:0xf
	v_mov_b32_dpp v114, v88 row_ror:1 row_mask:0xf bank_mask:0xf
	v_mov_b32_dpp v95, v88 row_ror:2 row_mask:0xf bank_mask:0xf
	v_mov_b32_dpp v115, v89 row_ror:1 row_mask:0xf bank_mask:0xf
	v_mov_b32_dpp v94, v89 row_ror:2 row_mask:0xf bank_mask:0xf
	v_mov_b32_dpp v57, v64 row_ror:1 row_mask:0xf bank_mask:0xf
	v_mov_b32_dpp v101, v64 row_ror:2 row_mask:0xf bank_mask:0xf
	v_mov_b32_dpp v116, v65 row_ror:1 row_mask:0xf bank_mask:0xf
	v_mov_b32_dpp v100, v65 row_ror:2 row_mask:0xf bank_mask:0xf
	v_mov_b32_dpp v117, v68 row_ror:1 row_mask:0xf bank_mask:0xf
	v_mov_b32_dpp v103, v68 row_ror:2 row_mask:0xf bank_mask:0xf
	v_mov_b32_dpp v118, v69 row_ror:1 row_mask:0xf bank_mask:0xf
	v_mov_b32_dpp v102, v69 row_ror:2 row_mask:0xf bank_mask:0xf
	v_cmp_gt_u32_e64 s[42:43], 2, v108
	v_lshl_add_u64 v[10:11], s[96:97], 0, v[22:23]
	v_lshl_add_u64 v[12:13], s[62:63], 0, v[22:23]
	global_load_dwordx4 v[18:21], v[10:11], off
	global_load_dwordx4 v[14:17], v[12:13], off
	v_lshl_add_u64 v[10:11], s[64:65], 0, v[22:23]
	v_lshl_add_u64 v[22:23], s[66:67], 0, v[22:23]
	global_load_dwordx4 v[10:13], v[10:11], off
	s_nop 1
	global_load_dwordx4 v[22:25], v[22:23], off
	s_nop 1
	v_mov_b32_dpp v70, v42 row_ror:1 row_mask:0xf bank_mask:0xf
	v_mov_b32_dpp v76, v42 row_ror:2 row_mask:0xf bank_mask:0xf
	v_mov_b32_dpp v71, v43 row_ror:1 row_mask:0xf bank_mask:0xf
	v_mov_b32_dpp v77, v43 row_ror:2 row_mask:0xf bank_mask:0xf
	v_mov_b32_dpp v74, v72 row_ror:1 row_mask:0xf bank_mask:0xf
	v_mov_b32_dpp v78, v72 row_ror:2 row_mask:0xf bank_mask:0xf
	v_mov_b32_dpp v75, v73 row_ror:1 row_mask:0xf bank_mask:0xf
	v_mov_b32_dpp v79, v73 row_ror:2 row_mask:0xf bank_mask:0xf
	s_and_saveexec_b64 s[0:1], s[42:43]
	s_xor_b64 s[0:1], exec, s[0:1]
	s_or_saveexec_b64 s[0:1], s[0:1]
	v_mov_b64_e32 v[106:107], v[98:99]
	v_mov_b64_e32 v[104:105], v[96:97]
	s_xor_b64 exec, exec, s[0:1]
	s_cbranch_execz .Lcg_skip3
	s_waitcnt vmcnt(4)
	v_pk_fma_f32 v[46:47], v[28:29], v[90:91], v[40:41] op_sel:[0,1,0] op_sel_hi:[1,0,1]
	v_mov_b64_e32 v[106:107], v[94:95]
	v_pk_fma_f32 v[46:47], v[32:33], v[80:81], v[46:47]
	v_mov_b64_e32 v[104:105], v[92:93]
	v_pk_fma_f32 v[46:47], v[84:85], v[36:37], v[46:47]
	v_pk_fma_f32 v[84:85], v[26:27], v[86:87], v[38:39] op_sel:[0,1,0] op_sel_hi:[1,0,1]
	v_pk_fma_f32 v[84:85], v[30:31], v[66:67], v[84:85]
	v_pk_fma_f32 v[44:45], v[44:45], v[34:35], v[84:85]
	v_pk_mul_f32 v[86:87], v[46:47], s[98:99] op_sel_hi:[1,0]
	v_exp_f32_e32 v86, v86
	v_exp_f32_e32 v87, v87
	s_nop 0
	v_pk_add_f32 v[86:87], v[86:87], 1.0 op_sel_hi:[1,0]
	v_rcp_f32_e32 v86, v86
	v_rcp_f32_e32 v87, v87
	s_nop 0
	v_pk_mul_f32 v[46:47], v[46:47], v[86:87]
	s_waitcnt vmcnt(0)
	v_pk_fma_f32 v[86:87], v[18:19], v[76:77], v[22:23]
	v_add_u32_e32 v53, 0x80, v56
	v_pk_fma_f32 v[86:87], v[14:15], v[70:71], v[86:87]
	v_pk_mul_f32 v[84:85], v[44:45], s[98:99] op_sel_hi:[1,0]
	v_exp_f32_e32 v84, v84
	v_exp_f32_e32 v85, v85
	s_nop 0
	v_pk_add_f32 v[84:85], v[84:85], 1.0 op_sel_hi:[1,0]
	v_rcp_f32_e32 v84, v84
	v_rcp_f32_e32 v85, v85
	s_nop 0
	v_pk_mul_f32 v[44:45], v[44:45], v[84:85]
	v_pk_fma_f32 v[42:43], v[42:43], v[10:11], v[86:87]
	v_pk_fma_f32 v[84:85], v[20:21], v[78:79], v[24:25]
	v_pk_mul_f32 v[42:43], v[44:45], v[42:43]
	v_mov_b64_e32 v[44:45], s[36:37]
	v_pk_fma_f32 v[84:85], v[16:17], v[74:75], v[84:85]
	v_mad_i64_i32 v[44:45], s[4:5], v53, s46, v[44:45]
	v_pk_fma_f32 v[72:73], v[72:73], v[12:13], v[84:85]
	v_lshl_add_u64 v[44:45], v[58:59], 1, v[44:45]
	v_mov_b64_e32 v[90:91], v[98:99]
	v_mov_b64_e32 v[86:87], v[96:97]
	v_mov_b64_e32 v[94:95], v[102:103]
	v_mov_b64_e32 v[92:93], v[100:101]
	v_pk_mul_f32 v[46:47], v[46:47], v[72:73]
	v_cvt_pk_bf16_f32 v238, v42, v43
	s_nop 0
	v_cvt_pk_bf16_f32 v239, v46, v47
	v_mov_b32_e32 v236, v228
	v_mov_b32_e32 v237, v229
	global_store_dwordx4 v[44:45], v[236:239], off offset:-8
.LBB0_135:
	s_or_b64 exec, exec, s[0:1]
	v_cmp_eq_u32_e64 s[42:43], 0, v108
	v_add_u32_e32 v96, 0x90, v56
	v_add_u32_e32 v97, 0xa0, v56
	v_add_u32_e32 v98, 0xb0, v56
	v_cndmask_b32_e64 v43, v118, v115, s[42:43]
	v_cndmask_b32_e64 v42, v117, v114, s[42:43]
	s_waitcnt vmcnt(4)
	v_pk_fma_f32 v[44:45], v[28:29], v[94:95], v[40:41] op_sel:[0,1,0] op_sel_hi:[1,0,1]
	v_cndmask_b32_e64 v47, v116, v113, s[42:43]
	v_cndmask_b32_e64 v46, v57, v112, s[42:43]
	v_pk_fma_f32 v[56:57], v[26:27], v[92:93], v[38:39] op_sel:[0,1,0] op_sel_hi:[1,0,1]
	v_pk_fma_f32 v[42:43], v[32:33], v[42:43], v[44:45]
	v_pk_fma_f32 v[46:47], v[30:31], v[46:47], v[56:57]
	v_pk_fma_f32 v[42:43], v[68:69], v[36:37], v[42:43]
	v_pk_fma_f32 v[46:47], v[64:65], v[34:35], v[46:47]
	v_cndmask_b32_e64 v65, v115, v111, s[42:43]
	v_cndmask_b32_e64 v64, v114, v110, s[42:43]
	v_pk_fma_f32 v[68:69], v[28:29], v[106:107], v[40:41] op_sel:[0,1,0] op_sel_hi:[1,0,1]
	v_cndmask_b32_e64 v81, v111, v81, s[42:43]
	v_cndmask_b32_e64 v80, v110, v80, s[42:43]
	v_pk_fma_f32 v[28:29], v[28:29], v[90:91], v[40:41] op_sel:[0,1,0] op_sel_hi:[1,0,1]
	v_pk_fma_f32 v[64:65], v[32:33], v[64:65], v[68:69]
	v_pk_fma_f32 v[28:29], v[32:33], v[80:81], v[28:29]
	v_pk_fma_f32 v[64:65], v[88:89], v[36:37], v[64:65]
	v_pk_fma_f32 v[84:85], v[26:27], v[104:105], v[38:39] op_sel:[0,1,0] op_sel_hi:[1,0,1]
	v_pk_fma_f32 v[28:29], v[60:61], v[36:37], v[28:29]
	v_cndmask_b32_e64 v37, v109, v67, s[42:43]
	v_cndmask_b32_e64 v36, v0, v66, s[42:43]
	v_pk_fma_f32 v[26:27], v[26:27], v[86:87], v[38:39] op_sel:[0,1,0] op_sel_hi:[1,0,1]
	v_cndmask_b32_e64 v72, v112, v0, s[42:43]
	v_pk_fma_f32 v[26:27], v[30:31], v[36:37], v[26:27]
	v_pk_fma_f32 v[26:27], v[54:55], v[34:35], v[26:27]
	v_cndmask_b32_e64 v73, v113, v109, s[42:43]
	v_pk_fma_f32 v[72:73], v[30:31], v[72:73], v[84:85]
	v_pk_fma_f32 v[72:73], v[82:83], v[34:35], v[72:73]
	v_mov_b32_e32 v34, v62
	v_mov_b32_e32 v35, v62
	v_mov_b32_e32 v53, v52
	v_mov_b32_e32 v63, v62
	v_pk_mul_f32 v[4:5], v[4:5], v[34:35]
	v_mov_b32_e32 v34, v52
	v_mov_b32_e32 v35, v52
	v_pk_mul_f32 v[2:3], v[2:3], v[62:63]
	v_pk_mul_f32 v[8:9], v[8:9], v[34:35]
	v_pk_mul_f32 v[6:7], v[6:7], v[52:53]
	s_nop 1
	v_mov_b32_dpp v52, v6 row_ror:2 row_mask:0xf bank_mask:0xf
	s_nop 1
	v_mov_b32_dpp v54, v7 row_ror:2 row_mask:0xf bank_mask:0xf
	s_nop 1
	v_mov_b32_dpp v60, v8 row_ror:2 row_mask:0xf bank_mask:0xf
	s_nop 1
	v_mov_b32_dpp v62, v9 row_ror:2 row_mask:0xf bank_mask:0xf
	v_mov_b32_dpp v0, v6 row_ror:1 row_mask:0xf bank_mask:0xf
	v_mov_b32_dpp v53, v7 row_ror:1 row_mask:0xf bank_mask:0xf
	v_mov_b32_dpp v55, v8 row_ror:1 row_mask:0xf bank_mask:0xf
	v_mov_b32_dpp v61, v9 row_ror:1 row_mask:0xf bank_mask:0xf
	v_cndmask_b32_e32 v34, v76, v52, vcc
	v_cndmask_b32_e32 v35, v77, v54, vcc
	v_cndmask_b32_e32 v36, v78, v60, vcc
	v_cndmask_b32_e32 v37, v79, v62, vcc
	v_cndmask_b32_e64 v38, v0, v70, s[42:43]
	v_cndmask_b32_e64 v39, v53, v71, s[42:43]
	v_cndmask_b32_e64 v40, v55, v74, s[42:43]
	v_cndmask_b32_e64 v41, v61, v75, s[42:43]
	v_pk_mul_f32 v[30:31], v[26:27], s[98:99] op_sel_hi:[1,0]
	v_pk_mul_f32 v[32:33], v[28:29], s[98:99] op_sel_hi:[1,0]
	v_exp_f32_e32 v30, v30
	v_exp_f32_e32 v31, v31
	v_exp_f32_e32 v32, v32
	v_exp_f32_e32 v33, v33
	v_pk_add_f32 v[30:31], v[30:31], 1.0 op_sel_hi:[1,0]
	v_pk_add_f32 v[32:33], v[32:33], 1.0 op_sel_hi:[1,0]
	v_rcp_f32_e32 v30, v30
	v_rcp_f32_e32 v31, v31
	v_rcp_f32_e32 v32, v32
	v_rcp_f32_e32 v33, v33
	v_pk_mul_f32 v[26:27], v[26:27], v[30:31]
	v_pk_mul_f32 v[28:29], v[28:29], v[32:33]
	s_waitcnt vmcnt(1)
	v_pk_fma_f32 v[30:31], v[20:21], v[36:37], v[24:25]
	v_pk_fma_f32 v[32:33], v[18:19], v[34:35], v[22:23]
	v_pk_fma_f32 v[30:31], v[16:17], v[40:41], v[30:31]
	v_pk_fma_f32 v[32:33], v[14:15], v[38:39], v[32:33]
	v_pk_fma_f32 v[8:9], v[8:9], v[12:13], v[30:31]
	v_pk_fma_f32 v[6:7], v[6:7], v[10:11], v[32:33]
	v_pk_mul_f32 v[8:9], v[28:29], v[8:9]
	v_pk_mul_f32 v[6:7], v[26:27], v[6:7]
	v_cvt_pk_bf16_f32 v238, v6, v7
	v_cvt_pk_bf16_f32 v239, v8, v9
	v_mov_b64_e32 v[8:9], s[36:37]
	v_mad_i64_i32 v[26:27], s[0:1], v96, s46, v[8:9]
	v_lshlrev_b64 v[28:29], 1, v[58:59]
	s_nop 1
	v_lshl_add_u64 v[26:27], v[26:27], 0, v[28:29]
	s_nop 1
	v_mov_b32_dpp v39, v2 row_ror:2 row_mask:0xf bank_mask:0xf
	s_nop 1
	v_mov_b32_dpp v41, v3 row_ror:2 row_mask:0xf bank_mask:0xf
	s_nop 1
	v_mov_b32_dpp v59, v4 row_ror:2 row_mask:0xf bank_mask:0xf
	s_nop 1
	v_mov_b32_dpp v66, v5 row_ror:2 row_mask:0xf bank_mask:0xf
	v_mov_b32_e32 v236, v230
	v_mov_b32_e32 v237, v231
	global_store_dwordx4 v[26:27], v[236:239], off offset:-8
	v_mov_b32_dpp v38, v2 row_ror:1 row_mask:0xf bank_mask:0xf
	v_mov_b32_dpp v40, v3 row_ror:1 row_mask:0xf bank_mask:0xf
	v_mov_b32_dpp v58, v4 row_ror:1 row_mask:0xf bank_mask:0xf
	v_mov_b32_dpp v63, v5 row_ror:1 row_mask:0xf bank_mask:0xf
	v_cndmask_b32_e32 v6, v52, v39, vcc
	v_cndmask_b32_e32 v7, v54, v41, vcc
	v_cndmask_b32_e32 v26, v60, v59, vcc
	v_cndmask_b32_e32 v27, v62, v66, vcc
	v_cndmask_b32_e64 v30, v38, v0, s[42:43]
	v_cndmask_b32_e64 v31, v40, v53, s[42:43]
	v_cndmask_b32_e64 v32, v58, v55, s[42:43]
	v_cndmask_b32_e64 v33, v63, v61, s[42:43]
	v_pk_fma_f32 v[26:27], v[20:21], v[26:27], v[24:25]
	v_pk_fma_f32 v[6:7], v[18:19], v[6:7], v[22:23]
	v_pk_fma_f32 v[26:27], v[16:17], v[32:33], v[26:27]
	v_pk_fma_f32 v[6:7], v[14:15], v[30:31], v[6:7]
	v_pk_mul_f32 v[82:83], v[72:73], s[98:99] op_sel_hi:[1,0]
	v_pk_mul_f32 v[68:69], v[64:65], s[98:99] op_sel_hi:[1,0]
	v_exp_f32_e32 v82, v82
	v_exp_f32_e32 v83, v83
	v_exp_f32_e32 v68, v68
	v_exp_f32_e32 v69, v69
	v_pk_add_f32 v[82:83], v[82:83], 1.0 op_sel_hi:[1,0]
	v_pk_add_f32 v[68:69], v[68:69], 1.0 op_sel_hi:[1,0]
	v_rcp_f32_e32 v82, v82
	v_rcp_f32_e32 v83, v83
	v_rcp_f32_e32 v68, v68
	v_rcp_f32_e32 v69, v69
	v_pk_mul_f32 v[34:35], v[72:73], v[82:83]
	v_pk_mul_f32 v[36:37], v[64:65], v[68:69]
	v_pk_fma_f32 v[4:5], v[4:5], v[12:13], v[26:27]
	v_pk_fma_f32 v[2:3], v[2:3], v[10:11], v[6:7]
	v_pk_mul_f32 v[4:5], v[36:37], v[4:5]
	v_pk_mul_f32 v[2:3], v[34:35], v[2:3]
	v_cvt_pk_bf16_f32 v238, v2, v3
	v_cvt_pk_bf16_f32 v239, v4, v5
	v_mad_i64_i32 v[4:5], s[0:1], v97, s46, v[8:9]
	v_lshl_add_u64 v[4:5], v[4:5], 0, v[28:29]
	v_mov_b32_e32 v236, v232
	v_mov_b32_e32 v237, v233
	global_store_dwordx4 v[4:5], v[236:239], off offset:-8
	s_nop 1
	s_nop 1
	v_mov_b32_dpp v2, v50 row_ror:2 row_mask:0xf bank_mask:0xf
	s_nop 1
	v_mov_b32_dpp v3, v51 row_ror:2 row_mask:0xf bank_mask:0xf
	s_nop 1
	v_mov_b32_dpp v4, v48 row_ror:2 row_mask:0xf bank_mask:0xf
	s_nop 1
	v_mov_b32_dpp v5, v49 row_ror:2 row_mask:0xf bank_mask:0xf
	v_mov_b32_dpp v0, v50 row_ror:1 row_mask:0xf bank_mask:0xf
	v_mov_b32_dpp v7, v51 row_ror:1 row_mask:0xf bank_mask:0xf
	v_mov_b32_dpp v26, v48 row_ror:1 row_mask:0xf bank_mask:0xf
	v_mov_b32_dpp v27, v49 row_ror:1 row_mask:0xf bank_mask:0xf
	v_cndmask_b32_e32 v2, v39, v2, vcc
	v_cndmask_b32_e32 v3, v41, v3, vcc
	v_cndmask_b32_e32 v4, v59, v4, vcc
	v_cndmask_b32_e32 v5, v66, v5, vcc
	v_cndmask_b32_e64 v6, v0, v38, s[42:43]
	v_cndmask_b32_e64 v7, v7, v40, s[42:43]
	v_cndmask_b32_e64 v26, v26, v58, s[42:43]
	v_cndmask_b32_e64 v27, v27, v63, s[42:43]
	v_pk_fma_f32 v[2:3], v[18:19], v[2:3], v[22:23]
	v_pk_fma_f32 v[4:5], v[20:21], v[4:5], v[24:25]
	v_pk_fma_f32 v[2:3], v[14:15], v[6:7], v[2:3]
	v_pk_fma_f32 v[4:5], v[16:17], v[26:27], v[4:5]
	v_pk_mul_f32 v[56:57], v[46:47], s[98:99] op_sel_hi:[1,0]
	v_pk_mul_f32 v[44:45], v[42:43], s[98:99] op_sel_hi:[1,0]
	v_exp_f32_e32 v56, v56
	v_exp_f32_e32 v57, v57
	v_exp_f32_e32 v44, v44
	v_exp_f32_e32 v45, v45
	v_pk_add_f32 v[56:57], v[56:57], 1.0 op_sel_hi:[1,0]
	v_pk_add_f32 v[44:45], v[44:45], 1.0 op_sel_hi:[1,0]
	v_rcp_f32_e32 v56, v56
	v_rcp_f32_e32 v57, v57
	v_rcp_f32_e32 v44, v44
	v_rcp_f32_e32 v45, v45
	v_pk_mul_f32 v[30:31], v[46:47], v[56:57]
	v_pk_mul_f32 v[32:33], v[42:43], v[44:45]
	v_pk_fma_f32 v[2:3], v[50:51], v[10:11], v[2:3]
	v_pk_fma_f32 v[4:5], v[48:49], v[12:13], v[4:5]
	v_pk_mul_f32 v[2:3], v[30:31], v[2:3]
	v_pk_mul_f32 v[4:5], v[32:33], v[4:5]
	v_cvt_pk_bf16_f32 v238, v2, v3
	s_nop 0
	v_cvt_pk_bf16_f32 v239, v4, v5
	v_mad_i64_i32 v[4:5], s[0:1], v98, s46, v[8:9]
	v_lshl_add_u64 v[4:5], v[4:5], 0, v[28:29]
	v_mov_b32_e32 v236, v234
	v_mov_b32_e32 v237, v235
	global_store_dwordx4 v[4:5], v[236:239], off offset:-8
	s_andn2_b64 vcc, exec, s[40:41]
	s_mov_b64 s[0:1], -1
	s_cbranch_vccnz .LBB0_102
	s_andn2_b64 vcc, exec, s[30:31]
	s_cbranch_vccnz .LBB0_101
	s_barrier
	s_branch .LBB0_101
